# scan y tree: levels 2 and 3 by two bank-masked DPP adds each (no selects), on the full stack
# baseline (speedup 1.0000x reference)
; #define LAS __attribute__((address_space(3)))
; __device__ __forceinline__ float row16_sum(float x) { x += dpp_mov<0xB1>(x); x += dpp_mov<0x4E>(x); x += dpp_mov<0x124>(x); x += dpp_mov<0x128>(x); return x; }
; __device__ __forceinline__ void scan_phase(const KAS Args& a, LAS unsigned char* lds, int i, const int tid_, const int bid, const int nblk) {
;     ...
;         for (int c = 0; c < T / TC; ++c) {
;             const bool more = (c + 1 < T / TC);
;             if (more) scan_load(Z, LO, mrow0, (c + 1) * TC, tid, colb, pz);
;             const LAS float* buf = bufs + (c & 1) * (TC * SST); LAS float* yb = ybuf + (c & 1) * (TC * 32);
;             {
;                 const LAS float* sb = buf + 4 * cgp; const LAS float* vb = buf + 320 + rl;
;                 f32x4 kk4 = *(const LAS f32x4*)(sb), nb4 = *(const LAS f32x4*)(sb + 64), w4 = *(const LAS f32x4*)(sb + 128), k4 = *(const LAS f32x4*)(sb + 192), r4 = *(const LAS f32x4*)(sb + 256);
;                 float v = vb[0], ysel = 0.f;
; #pragma unroll
;                 for (int t = 0; t < TC; ++t) {
;                     f32x4 kk4n = kk4, nb4n = nb4, w4n = w4, k4n = k4, r4n = r4; float vn = v;
;                     if (t + 1 < TC) { const LAS float* sn = sb + (t + 1) * SST;
;                         kk4n = *(const LAS f32x4*)(sn); nb4n = *(const LAS f32x4*)(sn + 64); w4n = *(const LAS f32x4*)(sn + 128); k4n = *(const LAS f32x4*)(sn + 192); r4n = *(const LAS f32x4*)(sn + 256); vn = vb[(t + 1) * SST]; }
;                     __builtin_amdgcn_sched_barrier(0x6);
;                     float sa = fmaf(S[3], kk4[3], fmaf(S[2], kk4[2], fmaf(S[1], kk4[1], S[0] * kk4[0])));
;                     const f32x4 Tm = S * w4 + k4 * v;
;                     sa = row16_sum(sa);
;                     S = Tm + nb4 * sa;
;                     float y = fmaf(S[3], r4[3], fmaf(S[2], r4[2], fmaf(S[1], r4[1], S[0] * r4[0]))); y = row16_sum(y);
;                     ysel = (cgp == (t & 15)) ? y : ysel;
;                     if ((t & 15) == 15) yb[(t - 15 + cgp) * 32 + rl] = ysel;
;                     kk4 = kk4n; nb4 = nb4n; w4 = w4n; k4 = k4n; r4 = r4n; v = vn; }
.LBB0_190:
	s_and_b32 s2, s67, 1
	s_mul_i32 s3, s2, 0xb000
	s_add_i32 s3, s94, s3
	v_add_u32_e32 v124, s3, v114
	v_add_u32_e32 v110, s3, v120
	ds_read_b128 v[136:139], v124 offset:0
	ds_read_b128 v[140:143], v124 offset:256
	ds_read_b128 v[144:147], v124 offset:512
	ds_read_b128 v[148:151], v124 offset:768
	ds_read_b128 v[152:155], v124 offset:1024
	ds_read_b32 v156, v110 offset:1280
	ds_read_b128 v[160:163], v124 offset:1408
	ds_read_b128 v[164:167], v124 offset:1664
	ds_read_b128 v[168:171], v124 offset:1920
	ds_read_b128 v[172:175], v124 offset:2176
	ds_read_b128 v[176:179], v124 offset:2432
	ds_read_b32 v158, v110 offset:2688
	ds_read_b128 v[188:191], v124 offset:2816
	ds_read_b128 v[192:195], v124 offset:3072
	ds_read_b128 v[196:199], v124 offset:3328
	ds_read_b128 v[200:203], v124 offset:3584
	ds_read_b128 v[204:207], v124 offset:3840
	ds_read_b32 v208, v110 offset:4096
	s_lshl_b32 s2, s2, 12
	s_add_i32 s63, s64, s2
	s_add_i32 s62, s67, 1
	s_andn2_b64 vcc, exec, s[60:61]
	v_add3_u32 v122, s63, v120, v118
	s_waitcnt lgkmcnt(12)
	v_mul_f32_e32 v44, v36, v136
	v_fmac_f32_e32 v44, v37, v137
	v_fmac_f32_e32 v44, v38, v138
	v_fmac_f32_e32 v44, v39, v139
	v_pk_mul_f32 v[40:41], v[148:149], v[156:157] op_sel_hi:[1,0]
	v_pk_mul_f32 v[42:43], v[150:151], v[156:157] op_sel_hi:[1,0]
	v_add_f32_dpp v2, v44, v44 quad_perm:[1,0,3,2] row_mask:0xf bank_mask:0xf bound_ctrl:1
	v_pk_fma_f32 v[40:41], v[36:37], v[144:145], v[40:41]
	v_pk_fma_f32 v[42:43], v[38:39], v[146:147], v[42:43]
	v_add_f32_dpp v2, v2, v2 quad_perm:[2,3,0,1] row_mask:0xf bank_mask:0xf bound_ctrl:1
	s_nop 0
	s_nop 0
	v_add_f32_dpp v2, v2, v2 row_ror:4 row_mask:0xf bank_mask:0xf bound_ctrl:1
	s_nop 0
	s_nop 0
	v_add_f32_dpp v2, v2, v2 row_ror:8 row_mask:0xf bank_mask:0xf bound_ctrl:1
	s_waitcnt lgkmcnt(6)
	v_pk_fma_f32 v[36:37], v[140:141], v[2:3], v[40:41] op_sel_hi:[1,0,1]
	v_pk_fma_f32 v[38:39], v[142:143], v[2:3], v[42:43] op_sel_hi:[1,0,1]
	v_mul_f32_e32 v44, v36, v160
	v_mul_f32_e32 v45, v152, v36
	v_fmac_f32_e32 v44, v37, v161
	v_fmac_f32_e32 v45, v37, v153
	v_fmac_f32_e32 v44, v38, v162
	v_fmac_f32_e32 v45, v38, v154
	v_fmac_f32_e32 v44, v39, v163
	v_fmac_f32_e32 v45, v39, v155
	v_pk_mul_f32 v[40:41], v[172:173], v[158:159] op_sel_hi:[1,0]
	v_pk_mul_f32 v[42:43], v[174:175], v[158:159] op_sel_hi:[1,0]
	v_add_f32_dpp v2, v44, v44 quad_perm:[1,0,3,2] row_mask:0xf bank_mask:0xf bound_ctrl:1
	v_pk_fma_f32 v[40:41], v[36:37], v[168:169], v[40:41]
	v_pk_fma_f32 v[42:43], v[38:39], v[170:171], v[42:43]
	v_add_f32_dpp v2, v2, v2 quad_perm:[2,3,0,1] row_mask:0xf bank_mask:0xf bound_ctrl:1
	ds_read_b128 v[136:139], v124 offset:4224
	ds_read_b128 v[140:143], v124 offset:4480
	ds_read_b128 v[144:147], v124 offset:4736
	v_add_f32_dpp v2, v2, v2 row_ror:4 row_mask:0xf bank_mask:0xf bound_ctrl:1
	ds_read_b128 v[148:151], v124 offset:4992
	ds_read_b128 v[152:155], v124 offset:5248
	ds_read_b32 v156, v110 offset:5504
	v_add_f32_dpp v2, v2, v2 row_ror:8 row_mask:0xf bank_mask:0xf bound_ctrl:1
	s_waitcnt lgkmcnt(6)
	v_pk_fma_f32 v[36:37], v[164:165], v[2:3], v[40:41] op_sel_hi:[1,0,1]
	v_pk_fma_f32 v[38:39], v[166:167], v[2:3], v[42:43] op_sel_hi:[1,0,1]
	v_mul_f32_e32 v44, v36, v188
	v_mul_f32_e32 v46, v176, v36
	v_fmac_f32_e32 v44, v37, v189
	v_fmac_f32_e32 v46, v37, v177
	v_fmac_f32_e32 v44, v38, v190
	v_fmac_f32_e32 v46, v38, v178
	v_fmac_f32_e32 v44, v39, v191
	v_fmac_f32_e32 v46, v39, v179
	v_pk_mul_f32 v[40:41], v[200:201], v[208:209] op_sel_hi:[1,0]
	v_pk_mul_f32 v[42:43], v[202:203], v[208:209] op_sel_hi:[1,0]
	v_add_f32_dpp v2, v44, v44 quad_perm:[1,0,3,2] row_mask:0xf bank_mask:0xf bound_ctrl:1
	v_pk_fma_f32 v[40:41], v[36:37], v[196:197], v[40:41]
	v_pk_fma_f32 v[42:43], v[38:39], v[198:199], v[42:43]
	v_add_f32_dpp v2, v2, v2 quad_perm:[2,3,0,1] row_mask:0xf bank_mask:0xf bound_ctrl:1
	ds_read_b128 v[160:163], v124 offset:5632
	ds_read_b128 v[164:167], v124 offset:5888
	ds_read_b128 v[168:171], v124 offset:6144
	v_add_f32_dpp v2, v2, v2 row_ror:4 row_mask:0xf bank_mask:0xf bound_ctrl:1
	ds_read_b128 v[172:175], v124 offset:6400
	ds_read_b128 v[176:179], v124 offset:6656
	ds_read_b32 v158, v110 offset:6912
	v_add_f32_dpp v2, v2, v2 row_ror:8 row_mask:0xf bank_mask:0xf bound_ctrl:1
	v_cndmask_b32_e64 v56, v45, v46, s[8:9]
	v_cndmask_b32_e64 v57, v46, v45, s[8:9]
	s_waitcnt lgkmcnt(6)
	v_pk_fma_f32 v[36:37], v[192:193], v[2:3], v[40:41] op_sel_hi:[1,0,1]
	v_pk_fma_f32 v[38:39], v[194:195], v[2:3], v[42:43] op_sel_hi:[1,0,1]
	v_add_f32_dpp v47, v57, v56 quad_perm:[1,0,3,2] row_mask:0xf bank_mask:0xf bound_ctrl:1
	v_mul_f32_e32 v44, v36, v136
	v_mul_f32_e32 v48, v204, v36
	v_fmac_f32_e32 v44, v37, v137
	v_fmac_f32_e32 v48, v37, v205
	v_fmac_f32_e32 v44, v38, v138
	v_fmac_f32_e32 v48, v38, v206
	v_fmac_f32_e32 v44, v39, v139
	v_fmac_f32_e32 v48, v39, v207
	v_pk_mul_f32 v[40:41], v[148:149], v[156:157] op_sel_hi:[1,0]
	v_pk_mul_f32 v[42:43], v[150:151], v[156:157] op_sel_hi:[1,0]
	v_add_f32_dpp v2, v44, v44 quad_perm:[1,0,3,2] row_mask:0xf bank_mask:0xf bound_ctrl:1
	v_pk_fma_f32 v[40:41], v[36:37], v[144:145], v[40:41]
	v_pk_fma_f32 v[42:43], v[38:39], v[146:147], v[42:43]
	v_add_f32_dpp v2, v2, v2 quad_perm:[2,3,0,1] row_mask:0xf bank_mask:0xf bound_ctrl:1
	ds_read_b128 v[188:191], v124 offset:7040
	ds_read_b128 v[192:195], v124 offset:7296
	ds_read_b128 v[196:199], v124 offset:7552
	v_add_f32_dpp v2, v2, v2 row_ror:4 row_mask:0xf bank_mask:0xf bound_ctrl:1
	ds_read_b128 v[200:203], v124 offset:7808
	ds_read_b128 v[204:207], v124 offset:8064
	ds_read_b32 v208, v110 offset:8320
	v_add_f32_dpp v2, v2, v2 row_ror:8 row_mask:0xf bank_mask:0xf bound_ctrl:1
	s_waitcnt lgkmcnt(6)
; #define LAS __attribute__((address_space(3)))
; __device__ __forceinline__ float row16_sum(float x) { x += dpp_mov<0xB1>(x); x += dpp_mov<0x4E>(x); x += dpp_mov<0x124>(x); x += dpp_mov<0x128>(x); return x; }
; __device__ __forceinline__ void up4(const u32x2 w, float (&f)[4]) { f[0] = bflo(w.x); f[1] = bfhi(w.x); f[2] = bflo(w.y); f[3] = bfhi(w.y); }
; __device__ __forceinline__ void scan_stage(const u32x2 (&pz)[8], LAS float* buf, float* RKB, size_t mrow0, int t0, int tid, int h, int half, ...
;     ...
;     up4(pz[0], zr); up4(pz[1], zk); up4(pz[2], zv); up4(pz[3], zrp); up4(pz[4], zkp); up4(pz[5], zvp); up4(pz[6], ew); up4(pz[7], ic);
;     f32x4 r, k2, v, kkv, w; float n2 = 0.f, rkb = 0.f;
; #pragma unroll
;     for (int e = 0; e < 4; ++e) { r[e] = zr[e] + (zrp[e] - zr[e]) * mu_r[e]; const float k = zk[e] + (zkp[e] - zk[e]) * mu_k[e]; v[e] = zv[e] + (zvp[e] - zv[e]) * mu_v[e];
;         kkv[e] = k * kkc[e]; n2 += kkv[e] * kkv[e]; k2[e] = k * (1.0f + (ic[e] - 1.0f) * kac[e]); w[e] = __builtin_amdgcn_exp2f(-1.4426950408889634f * ew[e]); rkb += r[e] * k2[e] * rkc[e]; }
; __device__ __forceinline__ void scan_phase(const KAS Args& a, LAS unsigned char* lds, int i, const int tid_, const int bid, const int nblk) {
;     ...
;                 for (int t = 0; t < TC; ++t) {
;                     f32x4 kk4n = kk4, nb4n = nb4, w4n = w4, k4n = k4, r4n = r4; float vn = v;
;                     if (t + 1 < TC) { const LAS float* sn = sb + (t + 1) * SST;
;                         kk4n = *(const LAS f32x4*)(sn); nb4n = *(const LAS f32x4*)(sn + 64); w4n = *(const LAS f32x4*)(sn + 128); k4n = *(const LAS f32x4*)(sn + 192); r4n = *(const LAS f32x4*)(sn + 256); vn = vb[(t + 1) * SST]; }
;                     __builtin_amdgcn_sched_barrier(0x6);
;                     float sa = fmaf(S[3], kk4[3], fmaf(S[2], kk4[2], fmaf(S[1], kk4[1], S[0] * kk4[0])));
;                     const f32x4 Tm = S * w4 + k4 * v;
;                     sa = row16_sum(sa);
;                     S = Tm + nb4 * sa;
;                     float y = fmaf(S[3], r4[3], fmaf(S[2], r4[2], fmaf(S[1], r4[1], S[0] * r4[0]))); y = row16_sum(y);
;                     ysel = (cgp == (t & 15)) ? y : ysel;
;                     if ((t & 15) == 15) yb[(t - 15 + cgp) * 32 + rl] = ysel;
;                     kk4 = kk4n; nb4 = nb4n; w4 = w4n; k4 = k4n; r4 = r4n; v = vn; }
	v_pk_fma_f32 v[36:37], v[140:141], v[2:3], v[40:41] op_sel_hi:[1,0,1]
	v_pk_fma_f32 v[38:39], v[142:143], v[2:3], v[42:43] op_sel_hi:[1,0,1]
	v_mul_f32_e32 v44, v36, v160
	v_mul_f32_e32 v49, v152, v36
	v_fmac_f32_e32 v44, v37, v161
	v_fmac_f32_e32 v49, v37, v153
	v_fmac_f32_e32 v44, v38, v162
	v_fmac_f32_e32 v49, v38, v154
	v_fmac_f32_e32 v44, v39, v163
	v_fmac_f32_e32 v49, v39, v155
	v_pk_mul_f32 v[40:41], v[172:173], v[158:159] op_sel_hi:[1,0]
	v_pk_mul_f32 v[42:43], v[174:175], v[158:159] op_sel_hi:[1,0]
	v_add_f32_dpp v2, v44, v44 quad_perm:[1,0,3,2] row_mask:0xf bank_mask:0xf bound_ctrl:1
	v_pk_fma_f32 v[40:41], v[36:37], v[168:169], v[40:41]
	v_pk_fma_f32 v[42:43], v[38:39], v[170:171], v[42:43]
	v_add_f32_dpp v2, v2, v2 quad_perm:[2,3,0,1] row_mask:0xf bank_mask:0xf bound_ctrl:1
	ds_read_b128 v[136:139], v124 offset:8448
	ds_read_b128 v[140:143], v124 offset:8704
	ds_read_b128 v[144:147], v124 offset:8960
	v_add_f32_dpp v2, v2, v2 row_ror:4 row_mask:0xf bank_mask:0xf bound_ctrl:1
	ds_read_b128 v[148:151], v124 offset:9216
	ds_read_b128 v[152:155], v124 offset:9472
	ds_read_b32 v156, v110 offset:9728
	v_add_f32_dpp v2, v2, v2 row_ror:8 row_mask:0xf bank_mask:0xf bound_ctrl:1
	v_cndmask_b32_e64 v56, v48, v49, s[8:9]
	v_cndmask_b32_e64 v57, v49, v48, s[8:9]
	s_waitcnt lgkmcnt(6)
	v_pk_fma_f32 v[36:37], v[164:165], v[2:3], v[40:41] op_sel_hi:[1,0,1]
	v_pk_fma_f32 v[38:39], v[166:167], v[2:3], v[42:43] op_sel_hi:[1,0,1]
	v_add_f32_dpp v50, v57, v56 quad_perm:[1,0,3,2] row_mask:0xf bank_mask:0xf bound_ctrl:1
	v_cndmask_b32_e64 v56, v47, v50, s[10:11]
	v_cndmask_b32_e64 v57, v50, v47, s[10:11]
	v_mul_f32_e32 v44, v36, v188
	v_mul_f32_e32 v52, v176, v36
	v_add_f32_dpp v51, v57, v56 quad_perm:[2,3,0,1] row_mask:0xf bank_mask:0xf bound_ctrl:1
	v_fmac_f32_e32 v44, v37, v189
	v_fmac_f32_e32 v52, v37, v177
	v_fmac_f32_e32 v44, v38, v190
	v_fmac_f32_e32 v52, v38, v178
	v_fmac_f32_e32 v44, v39, v191
	v_fmac_f32_e32 v52, v39, v179
	v_pk_mul_f32 v[40:41], v[200:201], v[208:209] op_sel_hi:[1,0]
	v_pk_mul_f32 v[42:43], v[202:203], v[208:209] op_sel_hi:[1,0]
	v_add_f32_dpp v2, v44, v44 quad_perm:[1,0,3,2] row_mask:0xf bank_mask:0xf bound_ctrl:1
	v_pk_fma_f32 v[40:41], v[36:37], v[196:197], v[40:41]
	v_pk_fma_f32 v[42:43], v[38:39], v[198:199], v[42:43]
	v_add_f32_dpp v2, v2, v2 quad_perm:[2,3,0,1] row_mask:0xf bank_mask:0xf bound_ctrl:1
	ds_read_b128 v[160:163], v124 offset:9856
	ds_read_b128 v[164:167], v124 offset:10112
	ds_read_b128 v[168:171], v124 offset:10368
	v_add_f32_dpp v2, v2, v2 row_ror:4 row_mask:0xf bank_mask:0xf bound_ctrl:1
	ds_read_b128 v[172:175], v124 offset:10624
	ds_read_b128 v[176:179], v124 offset:10880
	ds_read_b32 v158, v110 offset:11136
	v_add_f32_dpp v2, v2, v2 row_ror:8 row_mask:0xf bank_mask:0xf bound_ctrl:1
	s_waitcnt lgkmcnt(6)
	v_pk_fma_f32 v[36:37], v[192:193], v[2:3], v[40:41] op_sel_hi:[1,0,1]
	v_pk_fma_f32 v[38:39], v[194:195], v[2:3], v[42:43] op_sel_hi:[1,0,1]
	v_mul_f32_e32 v44, v36, v136
	v_mul_f32_e32 v53, v204, v36
	v_fmac_f32_e32 v44, v37, v137
	v_fmac_f32_e32 v53, v37, v205
	v_fmac_f32_e32 v44, v38, v138
	v_fmac_f32_e32 v53, v38, v206
	v_fmac_f32_e32 v44, v39, v139
	v_fmac_f32_e32 v53, v39, v207
	v_pk_mul_f32 v[40:41], v[148:149], v[156:157] op_sel_hi:[1,0]
	v_pk_mul_f32 v[42:43], v[150:151], v[156:157] op_sel_hi:[1,0]
	v_add_f32_dpp v2, v44, v44 quad_perm:[1,0,3,2] row_mask:0xf bank_mask:0xf bound_ctrl:1
	v_pk_fma_f32 v[40:41], v[36:37], v[144:145], v[40:41]
	v_pk_fma_f32 v[42:43], v[38:39], v[146:147], v[42:43]
	v_add_f32_dpp v2, v2, v2 quad_perm:[2,3,0,1] row_mask:0xf bank_mask:0xf bound_ctrl:1
	s_waitcnt vmcnt(4)
	v_lshlrev_b32_e32 v28, 16, v80
	ds_read_b128 v[188:191], v124 offset:11264
	ds_read_b128 v[192:195], v124 offset:11520
	ds_read_b128 v[196:199], v124 offset:11776
	v_add_f32_dpp v2, v2, v2 row_ror:4 row_mask:0xf bank_mask:0xf bound_ctrl:1
	ds_read_b128 v[200:203], v124 offset:12032
	ds_read_b128 v[204:207], v124 offset:12288
	ds_read_b32 v208, v110 offset:12544
	v_add_f32_dpp v2, v2, v2 row_ror:8 row_mask:0xf bank_mask:0xf bound_ctrl:1
	v_cndmask_b32_e64 v56, v52, v53, s[8:9]
	v_cndmask_b32_e64 v57, v53, v52, s[8:9]
	v_and_b32_e32 v29, 0xffff0000, v80
	v_lshlrev_b32_e32 v30, 16, v86
	s_waitcnt lgkmcnt(6)
	v_pk_fma_f32 v[36:37], v[140:141], v[2:3], v[40:41] op_sel_hi:[1,0,1]
	v_pk_fma_f32 v[38:39], v[142:143], v[2:3], v[42:43] op_sel_hi:[1,0,1]
	v_add_f32_dpp v54, v57, v56 quad_perm:[1,0,3,2] row_mask:0xf bank_mask:0xf bound_ctrl:1
	v_mul_f32_e32 v44, v36, v160
	v_mul_f32_e32 v55, v152, v36
	v_fmac_f32_e32 v44, v37, v161
	v_fmac_f32_e32 v55, v37, v153
	v_fmac_f32_e32 v44, v38, v162
	v_fmac_f32_e32 v55, v38, v154
	v_fmac_f32_e32 v44, v39, v163
	v_fmac_f32_e32 v55, v39, v155
	v_pk_mul_f32 v[40:41], v[172:173], v[158:159] op_sel_hi:[1,0]
	v_pk_mul_f32 v[42:43], v[174:175], v[158:159] op_sel_hi:[1,0]
	v_add_f32_dpp v2, v44, v44 quad_perm:[1,0,3,2] row_mask:0xf bank_mask:0xf bound_ctrl:1
	v_pk_fma_f32 v[40:41], v[36:37], v[168:169], v[40:41]
	v_pk_fma_f32 v[42:43], v[38:39], v[170:171], v[42:43]
	v_add_f32_dpp v2, v2, v2 quad_perm:[2,3,0,1] row_mask:0xf bank_mask:0xf bound_ctrl:1
	v_and_b32_e32 v31, 0xffff0000, v86
	v_pk_add_f32 v[30:31], v[30:31], v[28:29] neg_lo:[0,1] neg_hi:[0,1]
	ds_read_b128 v[136:139], v124 offset:12672
	ds_read_b128 v[140:143], v124 offset:12928
	ds_read_b128 v[144:147], v124 offset:13184
	v_add_f32_dpp v2, v2, v2 row_ror:4 row_mask:0xf bank_mask:0xf bound_ctrl:1
	ds_read_b128 v[148:151], v124 offset:13440
	ds_read_b128 v[152:155], v124 offset:13696
	ds_read_b32 v156, v110 offset:13952
	v_add_f32_dpp v2, v2, v2 row_ror:8 row_mask:0xf bank_mask:0xf bound_ctrl:1
	s_waitcnt vmcnt(3)
; #define LAS __attribute__((address_space(3)))
; __device__ __forceinline__ float row16_sum(float x) { x += dpp_mov<0xB1>(x); x += dpp_mov<0x4E>(x); x += dpp_mov<0x124>(x); x += dpp_mov<0x128>(x); return x; }
; __device__ __forceinline__ void up4(const u32x2 w, float (&f)[4]) { f[0] = bflo(w.x); f[1] = bfhi(w.x); f[2] = bflo(w.y); f[3] = bfhi(w.y); }
; __device__ __forceinline__ void scan_stage(const u32x2 (&pz)[8], LAS float* buf, float* RKB, size_t mrow0, int t0, int tid, int h, int half, ...
;     ...
;     up4(pz[0], zr); up4(pz[1], zk); up4(pz[2], zv); up4(pz[3], zrp); up4(pz[4], zkp); up4(pz[5], zvp); up4(pz[6], ew); up4(pz[7], ic);
;     f32x4 r, k2, v, kkv, w; float n2 = 0.f, rkb = 0.f;
; #pragma unroll
;     for (int e = 0; e < 4; ++e) { r[e] = zr[e] + (zrp[e] - zr[e]) * mu_r[e]; const float k = zk[e] + (zkp[e] - zk[e]) * mu_k[e]; v[e] = zv[e] + (zvp[e] - zv[e]) * mu_v[e];
;         kkv[e] = k * kkc[e]; n2 += kkv[e] * kkv[e]; k2[e] = k * (1.0f + (ic[e] - 1.0f) * kac[e]); w[e] = __builtin_amdgcn_exp2f(-1.4426950408889634f * ew[e]); rkb += r[e] * k2[e] * rkc[e]; }
; __device__ __forceinline__ void scan_phase(const KAS Args& a, LAS unsigned char* lds, int i, const int tid_, const int bid, const int nblk) {
;     ...
;                 for (int t = 0; t < TC; ++t) {
;                     f32x4 kk4n = kk4, nb4n = nb4, w4n = w4, k4n = k4, r4n = r4; float vn = v;
;                     if (t + 1 < TC) { const LAS float* sn = sb + (t + 1) * SST;
;                         kk4n = *(const LAS f32x4*)(sn); nb4n = *(const LAS f32x4*)(sn + 64); w4n = *(const LAS f32x4*)(sn + 128); k4n = *(const LAS f32x4*)(sn + 192); r4n = *(const LAS f32x4*)(sn + 256); vn = vb[(t + 1) * SST]; }
;                     __builtin_amdgcn_sched_barrier(0x6);
;                     float sa = fmaf(S[3], kk4[3], fmaf(S[2], kk4[2], fmaf(S[1], kk4[1], S[0] * kk4[0])));
;                     const f32x4 Tm = S * w4 + k4 * v;
;                     sa = row16_sum(sa);
;                     S = Tm + nb4 * sa;
;                     float y = fmaf(S[3], r4[3], fmaf(S[2], r4[2], fmaf(S[1], r4[1], S[0] * r4[0]))); y = row16_sum(y);
;                     ysel = (cgp == (t & 15)) ? y : ysel;
;                     if ((t & 15) == 15) yb[(t - 15 + cgp) * 32 + rl] = ysel;
;                     kk4 = kk4n; nb4 = nb4n; w4 = w4n; k4 = k4n; r4 = r4n; v = vn; }
	v_lshlrev_b32_e32 v32, 16, v88
	s_waitcnt lgkmcnt(6)
	v_pk_fma_f32 v[36:37], v[164:165], v[2:3], v[40:41] op_sel_hi:[1,0,1]
	v_pk_fma_f32 v[38:39], v[166:167], v[2:3], v[42:43] op_sel_hi:[1,0,1]
	v_mul_f32_e32 v44, v36, v188
	v_mul_f32_e32 v58, v176, v36
	v_fmac_f32_e32 v44, v37, v189
	v_fmac_f32_e32 v58, v37, v177
	v_fmac_f32_e32 v44, v38, v190
	v_fmac_f32_e32 v58, v38, v178
	v_fmac_f32_e32 v44, v39, v191
	v_fmac_f32_e32 v58, v39, v179
	v_pk_mul_f32 v[40:41], v[200:201], v[208:209] op_sel_hi:[1,0]
	v_pk_mul_f32 v[42:43], v[202:203], v[208:209] op_sel_hi:[1,0]
	v_add_f32_dpp v2, v44, v44 quad_perm:[1,0,3,2] row_mask:0xf bank_mask:0xf bound_ctrl:1
	v_pk_fma_f32 v[40:41], v[36:37], v[196:197], v[40:41]
	v_pk_fma_f32 v[42:43], v[38:39], v[198:199], v[42:43]
	v_add_f32_dpp v2, v2, v2 quad_perm:[2,3,0,1] row_mask:0xf bank_mask:0xf bound_ctrl:1
	v_pk_fma_f32 v[28:29], v[16:17], v[30:31], v[28:29]
	v_lshlrev_b32_e32 v30, 16, v82
	ds_read_b128 v[160:163], v124 offset:14080
	ds_read_b128 v[164:167], v124 offset:14336
	ds_read_b128 v[168:171], v124 offset:14592
	v_add_f32_dpp v2, v2, v2 row_ror:4 row_mask:0xf bank_mask:0xf bound_ctrl:1
	ds_read_b128 v[172:175], v124 offset:14848
	ds_read_b128 v[176:179], v124 offset:15104
	ds_read_b32 v158, v110 offset:15360
	v_add_f32_dpp v2, v2, v2 row_ror:8 row_mask:0xf bank_mask:0xf bound_ctrl:1
	v_cndmask_b32_e64 v56, v55, v58, s[8:9]
	v_cndmask_b32_e64 v57, v58, v55, s[8:9]
	v_and_b32_e32 v31, 0xffff0000, v82
	v_and_b32_e32 v33, 0xffff0000, v88
	s_waitcnt lgkmcnt(6)
	v_pk_fma_f32 v[36:37], v[192:193], v[2:3], v[40:41] op_sel_hi:[1,0,1]
	v_pk_fma_f32 v[38:39], v[194:195], v[2:3], v[42:43] op_sel_hi:[1,0,1]
	v_add_f32_dpp v59, v57, v56 quad_perm:[1,0,3,2] row_mask:0xf bank_mask:0xf bound_ctrl:1
	v_cndmask_b32_e64 v56, v54, v59, s[10:11]
	v_cndmask_b32_e64 v57, v59, v54, s[10:11]
	v_mul_f32_e32 v44, v36, v136
	v_mul_f32_e32 v62, v204, v36
	v_add_f32_dpp v60, v57, v56 quad_perm:[2,3,0,1] row_mask:0xf bank_mask:0xf bound_ctrl:1
	v_fmac_f32_e32 v44, v37, v137
	v_fmac_f32_e32 v62, v37, v205
	v_add_f32_dpp v61, v51, v51 row_shl:4 row_mask:0xf bank_mask:0x5
	v_fmac_f32_e32 v44, v38, v138
	v_fmac_f32_e32 v62, v38, v206
	v_add_f32_dpp v61, v60, v60 row_shr:4 row_mask:0xf bank_mask:0xa
	v_fmac_f32_e32 v44, v39, v139
	v_fmac_f32_e32 v62, v39, v207
	v_pk_mul_f32 v[40:41], v[148:149], v[156:157] op_sel_hi:[1,0]
	v_pk_mul_f32 v[42:43], v[150:151], v[156:157] op_sel_hi:[1,0]
	v_add_f32_dpp v2, v44, v44 quad_perm:[1,0,3,2] row_mask:0xf bank_mask:0xf bound_ctrl:1
	v_pk_fma_f32 v[40:41], v[36:37], v[144:145], v[40:41]
	v_pk_fma_f32 v[42:43], v[38:39], v[146:147], v[42:43]
	v_add_f32_dpp v2, v2, v2 quad_perm:[2,3,0,1] row_mask:0xf bank_mask:0xf bound_ctrl:1
	s_waitcnt vmcnt(0)
	v_lshlrev_b32_e32 v210, 16, v94
	ds_read_b128 v[188:191], v124 offset:15488
	ds_read_b128 v[192:195], v124 offset:15744
	ds_read_b128 v[196:199], v124 offset:16000
	v_add_f32_dpp v2, v2, v2 row_ror:4 row_mask:0xf bank_mask:0xf bound_ctrl:1
	ds_read_b128 v[200:203], v124 offset:16256
	ds_read_b128 v[204:207], v124 offset:16512
	ds_read_b32 v208, v110 offset:16768
	v_add_f32_dpp v2, v2, v2 row_ror:8 row_mask:0xf bank_mask:0xf bound_ctrl:1
	v_and_b32_e32 v211, 0xffff0000, v94
	v_pk_add_f32 v[32:33], v[32:33], v[30:31] neg_lo:[0,1] neg_hi:[0,1]
	s_waitcnt lgkmcnt(6)
	v_pk_fma_f32 v[36:37], v[140:141], v[2:3], v[40:41] op_sel_hi:[1,0,1]
	v_pk_fma_f32 v[38:39], v[142:143], v[2:3], v[42:43] op_sel_hi:[1,0,1]
	v_mul_f32_e32 v44, v36, v160
	v_mul_f32_e32 v63, v152, v36
	v_fmac_f32_e32 v44, v37, v161
	v_fmac_f32_e32 v63, v37, v153
	v_fmac_f32_e32 v44, v38, v162
	v_fmac_f32_e32 v63, v38, v154
	v_fmac_f32_e32 v44, v39, v163
	v_fmac_f32_e32 v63, v39, v155
	v_pk_mul_f32 v[40:41], v[172:173], v[158:159] op_sel_hi:[1,0]
	v_pk_mul_f32 v[42:43], v[174:175], v[158:159] op_sel_hi:[1,0]
	v_add_f32_dpp v2, v44, v44 quad_perm:[1,0,3,2] row_mask:0xf bank_mask:0xf bound_ctrl:1
	v_pk_fma_f32 v[40:41], v[36:37], v[168:169], v[40:41]
	v_pk_fma_f32 v[42:43], v[38:39], v[170:171], v[42:43]
	v_add_f32_dpp v2, v2, v2 quad_perm:[2,3,0,1] row_mask:0xf bank_mask:0xf bound_ctrl:1
	v_lshlrev_b32_e32 v216, 16, v89
	v_pk_fma_f32 v[30:31], v[20:21], v[32:33], v[30:31]
	ds_read_b128 v[136:139], v124 offset:16896
	ds_read_b128 v[140:143], v124 offset:17152
	ds_read_b128 v[144:147], v124 offset:17408
	v_add_f32_dpp v2, v2, v2 row_ror:4 row_mask:0xf bank_mask:0xf bound_ctrl:1
	ds_read_b128 v[148:151], v124 offset:17664
	ds_read_b128 v[152:155], v124 offset:17920
	ds_read_b32 v156, v110 offset:18176
	v_add_f32_dpp v2, v2, v2 row_ror:8 row_mask:0xf bank_mask:0xf bound_ctrl:1
	v_cndmask_b32_e64 v56, v62, v63, s[8:9]
	v_cndmask_b32_e64 v57, v63, v62, s[8:9]
	v_pk_add_f32 v[32:33], v[210:211], -1.0 op_sel_hi:[1,0]
	v_pk_mul_f32 v[212:213], v[12:13], v[30:31]
	s_waitcnt lgkmcnt(6)
	v_pk_fma_f32 v[36:37], v[164:165], v[2:3], v[40:41] op_sel_hi:[1,0,1]
	v_pk_fma_f32 v[38:39], v[166:167], v[2:3], v[42:43] op_sel_hi:[1,0,1]
	v_add_f32_dpp v64, v57, v56 quad_perm:[1,0,3,2] row_mask:0xf bank_mask:0xf bound_ctrl:1
	v_mul_f32_e32 v44, v36, v188
	v_mul_f32_e32 v65, v176, v36
	v_fmac_f32_e32 v44, v37, v189
	v_fmac_f32_e32 v65, v37, v177
	v_fmac_f32_e32 v44, v38, v190
	v_fmac_f32_e32 v65, v38, v178
	v_fmac_f32_e32 v44, v39, v191
	v_fmac_f32_e32 v65, v39, v179
	v_pk_mul_f32 v[40:41], v[200:201], v[208:209] op_sel_hi:[1,0]
	v_pk_mul_f32 v[42:43], v[202:203], v[208:209] op_sel_hi:[1,0]
	v_add_f32_dpp v2, v44, v44 quad_perm:[1,0,3,2] row_mask:0xf bank_mask:0xf bound_ctrl:1
	v_pk_fma_f32 v[40:41], v[36:37], v[196:197], v[40:41]
	v_pk_fma_f32 v[42:43], v[38:39], v[198:199], v[42:43]
	v_add_f32_dpp v2, v2, v2 quad_perm:[2,3,0,1] row_mask:0xf bank_mask:0xf bound_ctrl:1
	v_pk_fma_f32 v[32:33], v[24:25], v[32:33], 1.0 op_sel_hi:[1,1,0]
	v_and_b32_e32 v217, 0xffff0000, v89
	ds_read_b128 v[160:163], v124 offset:18304
	ds_read_b128 v[164:167], v124 offset:18560
	ds_read_b128 v[168:171], v124 offset:18816
	v_add_f32_dpp v2, v2, v2 row_ror:4 row_mask:0xf bank_mask:0xf bound_ctrl:1
	ds_read_b128 v[172:175], v124 offset:19072
	ds_read_b128 v[176:179], v124 offset:19328
	ds_read_b32 v158, v110 offset:19584
	v_add_f32_dpp v2, v2, v2 row_ror:8 row_mask:0xf bank_mask:0xf bound_ctrl:1
	v_pk_mul_f32 v[32:33], v[30:31], v[32:33]
	v_lshlrev_b32_e32 v30, 16, v81
	s_waitcnt lgkmcnt(6)
; #define LAS __attribute__((address_space(3)))
; __device__ __forceinline__ float row16_sum(float x) { x += dpp_mov<0xB1>(x); x += dpp_mov<0x4E>(x); x += dpp_mov<0x124>(x); x += dpp_mov<0x128>(x); return x; }
; __device__ __forceinline__ void scan_stage(const u32x2 (&pz)[8], LAS float* buf, float* RKB, size_t mrow0, int t0, int tid, int h, int half, ...
;     ...
;     for (int e = 0; e < 4; ++e) { r[e] = zr[e] + (zrp[e] - zr[e]) * mu_r[e]; const float k = zk[e] + (zkp[e] - zk[e]) * mu_k[e]; v[e] = zv[e] + (zvp[e] - zv[e]) * mu_v[e];
;         kkv[e] = k * kkc[e]; n2 += kkv[e] * kkv[e]; k2[e] = k * (1.0f + (ic[e] - 1.0f) * kac[e]); w[e] = __builtin_amdgcn_exp2f(-1.4426950408889634f * ew[e]); rkb += r[e] * k2[e] * rkc[e]; }
; __device__ __forceinline__ void scan_phase(const KAS Args& a, LAS unsigned char* lds, int i, const int tid_, const int bid, const int nblk) {
;     ...
;                 for (int t = 0; t < TC; ++t) {
;                     f32x4 kk4n = kk4, nb4n = nb4, w4n = w4, k4n = k4, r4n = r4; float vn = v;
;                     if (t + 1 < TC) { const LAS float* sn = sb + (t + 1) * SST;
;                         kk4n = *(const LAS f32x4*)(sn); nb4n = *(const LAS f32x4*)(sn + 64); w4n = *(const LAS f32x4*)(sn + 128); k4n = *(const LAS f32x4*)(sn + 192); r4n = *(const LAS f32x4*)(sn + 256); vn = vb[(t + 1) * SST]; }
;                     __builtin_amdgcn_sched_barrier(0x6);
;                     float sa = fmaf(S[3], kk4[3], fmaf(S[2], kk4[2], fmaf(S[1], kk4[1], S[0] * kk4[0])));
;                     const f32x4 Tm = S * w4 + k4 * v;
;                     sa = row16_sum(sa);
;                     S = Tm + nb4 * sa;
;                     float y = fmaf(S[3], r4[3], fmaf(S[2], r4[2], fmaf(S[1], r4[1], S[0] * r4[0]))); y = row16_sum(y);
;                     ysel = (cgp == (t & 15)) ? y : ysel;
;                     if ((t & 15) == 15) yb[(t - 15 + cgp) * 32 + rl] = ysel;
;                     kk4 = kk4n; nb4 = nb4n; w4 = w4n; k4 = k4n; r4 = r4n; v = vn; }
	v_pk_fma_f32 v[36:37], v[192:193], v[2:3], v[40:41] op_sel_hi:[1,0,1]
	v_pk_fma_f32 v[38:39], v[194:195], v[2:3], v[42:43] op_sel_hi:[1,0,1]
	v_mul_f32_e32 v44, v36, v136
	v_mul_f32_e32 v66, v204, v36
	v_fmac_f32_e32 v44, v37, v137
	v_fmac_f32_e32 v66, v37, v205
	v_fmac_f32_e32 v44, v38, v138
	v_fmac_f32_e32 v66, v38, v206
	v_fmac_f32_e32 v44, v39, v139
	v_fmac_f32_e32 v66, v39, v207
	v_pk_mul_f32 v[40:41], v[148:149], v[156:157] op_sel_hi:[1,0]
	v_pk_mul_f32 v[42:43], v[150:151], v[156:157] op_sel_hi:[1,0]
	v_add_f32_dpp v2, v44, v44 quad_perm:[1,0,3,2] row_mask:0xf bank_mask:0xf bound_ctrl:1
	v_pk_fma_f32 v[40:41], v[36:37], v[144:145], v[40:41]
	v_pk_fma_f32 v[42:43], v[38:39], v[146:147], v[42:43]
	v_add_f32_dpp v2, v2, v2 quad_perm:[2,3,0,1] row_mask:0xf bank_mask:0xf bound_ctrl:1
	v_pk_mul_f32 v[34:35], v[28:29], v[32:33]
	v_and_b32_e32 v31, 0xffff0000, v81
	ds_read_b128 v[188:191], v124 offset:19712
	ds_read_b128 v[192:195], v124 offset:19968
	ds_read_b128 v[196:199], v124 offset:20224
	v_add_f32_dpp v2, v2, v2 row_ror:4 row_mask:0xf bank_mask:0xf bound_ctrl:1
	ds_read_b128 v[200:203], v124 offset:20480
	ds_read_b128 v[204:207], v124 offset:20736
	ds_read_b32 v208, v110 offset:20992
	v_add_f32_dpp v2, v2, v2 row_ror:8 row_mask:0xf bank_mask:0xf bound_ctrl:1
	v_cndmask_b32_e64 v56, v65, v66, s[8:9]
	v_cndmask_b32_e64 v57, v66, v65, s[8:9]
	v_fma_f32 v224, v4, v34, 0
	v_fmac_f32_e32 v224, v5, v35
	s_waitcnt lgkmcnt(6)
	v_pk_fma_f32 v[36:37], v[140:141], v[2:3], v[40:41] op_sel_hi:[1,0,1]
	v_pk_fma_f32 v[38:39], v[142:143], v[2:3], v[42:43] op_sel_hi:[1,0,1]
	v_add_f32_dpp v67, v57, v56 quad_perm:[1,0,3,2] row_mask:0xf bank_mask:0xf bound_ctrl:1
	v_cndmask_b32_e64 v56, v64, v67, s[10:11]
	v_cndmask_b32_e64 v57, v67, v64, s[10:11]
	v_mul_f32_e32 v44, v36, v160
	v_mul_f32_e32 v46, v152, v36
	v_add_f32_dpp v45, v57, v56 quad_perm:[2,3,0,1] row_mask:0xf bank_mask:0xf bound_ctrl:1
	v_fmac_f32_e32 v44, v37, v161
	v_fmac_f32_e32 v46, v37, v153
	v_fmac_f32_e32 v44, v38, v162
	v_fmac_f32_e32 v46, v38, v154
	v_fmac_f32_e32 v44, v39, v163
	v_fmac_f32_e32 v46, v39, v155
	v_pk_mul_f32 v[40:41], v[172:173], v[158:159] op_sel_hi:[1,0]
	v_pk_mul_f32 v[42:43], v[174:175], v[158:159] op_sel_hi:[1,0]
	v_add_f32_dpp v2, v44, v44 quad_perm:[1,0,3,2] row_mask:0xf bank_mask:0xf bound_ctrl:1
	v_pk_fma_f32 v[40:41], v[36:37], v[168:169], v[40:41]
	v_pk_fma_f32 v[42:43], v[38:39], v[170:171], v[42:43]
	v_add_f32_dpp v2, v2, v2 quad_perm:[2,3,0,1] row_mask:0xf bank_mask:0xf bound_ctrl:1
	v_lshlrev_b32_e32 v34, 16, v87
	v_and_b32_e32 v35, 0xffff0000, v87
	ds_read_b128 v[136:139], v124 offset:21120
	ds_read_b128 v[140:143], v124 offset:21376
	ds_read_b128 v[144:147], v124 offset:21632
	v_add_f32_dpp v2, v2, v2 row_ror:4 row_mask:0xf bank_mask:0xf bound_ctrl:1
	ds_read_b128 v[148:151], v124 offset:21888
	ds_read_b128 v[152:155], v124 offset:22144
	ds_read_b32 v156, v110 offset:22400
	v_add_f32_dpp v2, v2, v2 row_ror:8 row_mask:0xf bank_mask:0xf bound_ctrl:1
	v_pk_add_f32 v[34:35], v[34:35], v[30:31] neg_lo:[0,1] neg_hi:[0,1]
	v_lshlrev_b32_e32 v214, 16, v95
	s_waitcnt lgkmcnt(6)
	v_pk_fma_f32 v[36:37], v[164:165], v[2:3], v[40:41] op_sel_hi:[1,0,1]
	v_pk_fma_f32 v[38:39], v[166:167], v[2:3], v[42:43] op_sel_hi:[1,0,1]
	v_mul_f32_e32 v44, v36, v188
	v_mul_f32_e32 v48, v176, v36
	v_fmac_f32_e32 v44, v37, v189
	v_fmac_f32_e32 v48, v37, v177
	v_fmac_f32_e32 v44, v38, v190
	v_fmac_f32_e32 v48, v38, v178
	v_fmac_f32_e32 v44, v39, v191
	v_fmac_f32_e32 v48, v39, v179
	v_pk_mul_f32 v[40:41], v[200:201], v[208:209] op_sel_hi:[1,0]
	v_pk_mul_f32 v[42:43], v[202:203], v[208:209] op_sel_hi:[1,0]
	v_add_f32_dpp v2, v44, v44 quad_perm:[1,0,3,2] row_mask:0xf bank_mask:0xf bound_ctrl:1
	v_pk_fma_f32 v[40:41], v[36:37], v[196:197], v[40:41]
	v_pk_fma_f32 v[42:43], v[38:39], v[198:199], v[42:43]
	v_add_f32_dpp v2, v2, v2 quad_perm:[2,3,0,1] row_mask:0xf bank_mask:0xf bound_ctrl:1
	v_pk_fma_f32 v[30:31], v[18:19], v[34:35], v[30:31]
	v_lshlrev_b32_e32 v34, 16, v83
	ds_read_b128 v[160:163], v124 offset:22528
	ds_read_b128 v[164:167], v124 offset:22784
	ds_read_b128 v[168:171], v124 offset:23040
	v_add_f32_dpp v2, v2, v2 row_ror:4 row_mask:0xf bank_mask:0xf bound_ctrl:1
	ds_read_b128 v[172:175], v124 offset:23296
	ds_read_b128 v[176:179], v124 offset:23552
	ds_read_b32 v158, v110 offset:23808
	v_add_f32_dpp v2, v2, v2 row_ror:8 row_mask:0xf bank_mask:0xf bound_ctrl:1
	v_cndmask_b32_e64 v56, v46, v48, s[8:9]
	v_cndmask_b32_e64 v57, v48, v46, s[8:9]
	v_and_b32_e32 v35, 0xffff0000, v83
	v_and_b32_e32 v215, 0xffff0000, v95
	s_waitcnt lgkmcnt(6)
	v_pk_fma_f32 v[36:37], v[192:193], v[2:3], v[40:41] op_sel_hi:[1,0,1]
	v_pk_fma_f32 v[38:39], v[194:195], v[2:3], v[42:43] op_sel_hi:[1,0,1]
	v_add_f32_dpp v49, v57, v56 quad_perm:[1,0,3,2] row_mask:0xf bank_mask:0xf bound_ctrl:1
	v_mul_f32_e32 v44, v36, v136
	v_mul_f32_e32 v47, v204, v36
	v_fmac_f32_e32 v44, v37, v137
	v_fmac_f32_e32 v47, v37, v205
	v_fmac_f32_e32 v44, v38, v138
	v_fmac_f32_e32 v47, v38, v206
	v_fmac_f32_e32 v44, v39, v139
	v_fmac_f32_e32 v47, v39, v207
	v_pk_mul_f32 v[40:41], v[148:149], v[156:157] op_sel_hi:[1,0]
	v_pk_mul_f32 v[42:43], v[150:151], v[156:157] op_sel_hi:[1,0]
	v_add_f32_dpp v2, v44, v44 quad_perm:[1,0,3,2] row_mask:0xf bank_mask:0xf bound_ctrl:1
	v_pk_fma_f32 v[40:41], v[36:37], v[144:145], v[40:41]
	v_pk_fma_f32 v[42:43], v[38:39], v[146:147], v[42:43]
	v_add_f32_dpp v2, v2, v2 quad_perm:[2,3,0,1] row_mask:0xf bank_mask:0xf bound_ctrl:1
	v_pk_add_f32 v[216:217], v[216:217], v[34:35] neg_lo:[0,1] neg_hi:[0,1]
	v_pk_mul_f32 v[218:219], v[212:213], v[212:213]
	ds_read_b128 v[188:191], v124 offset:23936
	ds_read_b128 v[192:195], v124 offset:24192
	ds_read_b128 v[196:199], v124 offset:24448
	v_add_f32_dpp v2, v2, v2 row_ror:4 row_mask:0xf bank_mask:0xf bound_ctrl:1
	ds_read_b128 v[200:203], v124 offset:24704
	ds_read_b128 v[204:207], v124 offset:24960
	ds_read_b32 v208, v110 offset:25216
	v_add_f32_dpp v2, v2, v2 row_ror:8 row_mask:0xf bank_mask:0xf bound_ctrl:1
	v_pk_fma_f32 v[216:217], v[22:23], v[216:217], v[34:35]
	v_pk_add_f32 v[34:35], v[214:215], -1.0 op_sel_hi:[1,0]
	s_waitcnt lgkmcnt(6)
; #define LAS __attribute__((address_space(3)))
; __device__ __forceinline__ float row16_sum(float x) { x += dpp_mov<0xB1>(x); x += dpp_mov<0x4E>(x); x += dpp_mov<0x124>(x); x += dpp_mov<0x128>(x); return x; }
; __device__ __forceinline__ void scan_stage(const u32x2 (&pz)[8], LAS float* buf, float* RKB, size_t mrow0, int t0, int tid, int h, int half, ...
;     ...
;     for (int e = 0; e < 4; ++e) { r[e] = zr[e] + (zrp[e] - zr[e]) * mu_r[e]; const float k = zk[e] + (zkp[e] - zk[e]) * mu_k[e]; v[e] = zv[e] + (zvp[e] - zv[e]) * mu_v[e];
;         kkv[e] = k * kkc[e]; n2 += kkv[e] * kkv[e]; k2[e] = k * (1.0f + (ic[e] - 1.0f) * kac[e]); w[e] = __builtin_amdgcn_exp2f(-1.4426950408889634f * ew[e]); rkb += r[e] * k2[e] * rkc[e]; }
; __device__ __forceinline__ void scan_phase(const KAS Args& a, LAS unsigned char* lds, int i, const int tid_, const int bid, const int nblk) {
;     ...
;                 for (int t = 0; t < TC; ++t) {
;                     f32x4 kk4n = kk4, nb4n = nb4, w4n = w4, k4n = k4, r4n = r4; float vn = v;
;                     if (t + 1 < TC) { const LAS float* sn = sb + (t + 1) * SST;
;                         kk4n = *(const LAS f32x4*)(sn); nb4n = *(const LAS f32x4*)(sn + 64); w4n = *(const LAS f32x4*)(sn + 128); k4n = *(const LAS f32x4*)(sn + 192); r4n = *(const LAS f32x4*)(sn + 256); vn = vb[(t + 1) * SST]; }
;                     __builtin_amdgcn_sched_barrier(0x6);
;                     float sa = fmaf(S[3], kk4[3], fmaf(S[2], kk4[2], fmaf(S[1], kk4[1], S[0] * kk4[0])));
;                     const f32x4 Tm = S * w4 + k4 * v;
;                     sa = row16_sum(sa);
;                     S = Tm + nb4 * sa;
;                     float y = fmaf(S[3], r4[3], fmaf(S[2], r4[2], fmaf(S[1], r4[1], S[0] * r4[0]))); y = row16_sum(y);
;                     ysel = (cgp == (t & 15)) ? y : ysel;
;                     if ((t & 15) == 15) yb[(t - 15 + cgp) * 32 + rl] = ysel;
;                     kk4 = kk4n; nb4 = nb4n; w4 = w4n; k4 = k4n; r4 = r4n; v = vn; }
	v_pk_fma_f32 v[36:37], v[140:141], v[2:3], v[40:41] op_sel_hi:[1,0,1]
	v_pk_fma_f32 v[38:39], v[142:143], v[2:3], v[42:43] op_sel_hi:[1,0,1]
	v_mul_f32_e32 v44, v36, v160
	v_mul_f32_e32 v50, v152, v36
	v_fmac_f32_e32 v44, v37, v161
	v_fmac_f32_e32 v50, v37, v153
	v_fmac_f32_e32 v44, v38, v162
	v_fmac_f32_e32 v50, v38, v154
	v_fmac_f32_e32 v44, v39, v163
	v_fmac_f32_e32 v50, v39, v155
	v_pk_mul_f32 v[40:41], v[172:173], v[158:159] op_sel_hi:[1,0]
	v_pk_mul_f32 v[42:43], v[174:175], v[158:159] op_sel_hi:[1,0]
	v_add_f32_dpp v2, v44, v44 quad_perm:[1,0,3,2] row_mask:0xf bank_mask:0xf bound_ctrl:1
	v_pk_fma_f32 v[40:41], v[36:37], v[168:169], v[40:41]
	v_pk_fma_f32 v[42:43], v[38:39], v[170:171], v[42:43]
	v_add_f32_dpp v2, v2, v2 quad_perm:[2,3,0,1] row_mask:0xf bank_mask:0xf bound_ctrl:1
	v_add_f32_e32 v228, v218, v219
	v_pk_fma_f32 v[34:35], v[26:27], v[34:35], 1.0 op_sel_hi:[1,1,0]
	ds_read_b128 v[136:139], v124 offset:25344
	ds_read_b128 v[140:143], v124 offset:25600
	ds_read_b128 v[144:147], v124 offset:25856
	v_add_f32_dpp v2, v2, v2 row_ror:4 row_mask:0xf bank_mask:0xf bound_ctrl:1
	ds_read_b128 v[148:151], v124 offset:26112
	ds_read_b128 v[152:155], v124 offset:26368
	ds_read_b32 v156, v110 offset:26624
	v_add_f32_dpp v2, v2, v2 row_ror:8 row_mask:0xf bank_mask:0xf bound_ctrl:1
	v_cndmask_b32_e64 v56, v47, v50, s[8:9]
	v_cndmask_b32_e64 v57, v50, v47, s[8:9]
	v_mov_b32_e32 v218, 0
	v_pk_mul_f32 v[34:35], v[216:217], v[34:35]
	v_add_f32_dpp v52, v57, v56 quad_perm:[1,0,3,2] row_mask:0xf bank_mask:0xf bound_ctrl:1
	v_cndmask_b32_e64 v56, v49, v52, s[10:11]
	v_cndmask_b32_e64 v57, v52, v49, s[10:11]
	s_nop 0
	s_nop 0
	v_add_f32_dpp v53, v57, v56 quad_perm:[2,3,0,1] row_mask:0xf bank_mask:0xf bound_ctrl:1
	v_add_f32_dpp v55, v45, v45 row_shl:4 row_mask:0xf bank_mask:0x5
	s_nop 0
	s_nop 0
	v_add_f32_dpp v55, v53, v53 row_shr:4 row_mask:0xf bank_mask:0xa
	v_add_f32_dpp v58, v61, v61 row_ror:8 row_mask:0xf bank_mask:0x3
	s_nop 0
	s_nop 0
	v_add_f32_dpp v58, v55, v55 row_ror:8 row_mask:0xf bank_mask:0xc
	ds_write_b32 v122, v58
	s_waitcnt lgkmcnt(7)
	v_pk_fma_f32 v[36:37], v[164:165], v[2:3], v[40:41] op_sel_hi:[1,0,1]
	v_pk_fma_f32 v[38:39], v[166:167], v[2:3], v[42:43] op_sel_hi:[1,0,1]
	v_mul_f32_e32 v44, v36, v188
	v_mul_f32_e32 v54, v176, v36
	v_fmac_f32_e32 v44, v37, v189
	v_fmac_f32_e32 v54, v37, v177
	v_fmac_f32_e32 v44, v38, v190
	v_fmac_f32_e32 v54, v38, v178
	v_fmac_f32_e32 v44, v39, v191
	v_fmac_f32_e32 v54, v39, v179
	v_pk_mul_f32 v[40:41], v[200:201], v[208:209] op_sel_hi:[1,0]
	v_pk_mul_f32 v[42:43], v[202:203], v[208:209] op_sel_hi:[1,0]
	v_add_f32_dpp v2, v44, v44 quad_perm:[1,0,3,2] row_mask:0xf bank_mask:0xf bound_ctrl:1
	v_pk_fma_f32 v[40:41], v[36:37], v[196:197], v[40:41]
	v_pk_fma_f32 v[42:43], v[38:39], v[198:199], v[42:43]
	v_add_f32_dpp v2, v2, v2 quad_perm:[2,3,0,1] row_mask:0xf bank_mask:0xf bound_ctrl:1
	v_pk_mul_f32 v[216:217], v[14:15], v[216:217]
	v_pk_mul_f32 v[220:221], v[30:31], v[34:35]
	ds_read_b128 v[160:163], v124 offset:26752
	ds_read_b128 v[164:167], v124 offset:27008
	ds_read_b128 v[168:171], v124 offset:27264
	v_add_f32_dpp v2, v2, v2 row_ror:4 row_mask:0xf bank_mask:0xf bound_ctrl:1
	ds_read_b128 v[172:175], v124 offset:27520
	ds_read_b128 v[176:179], v124 offset:27776
	ds_read_b32 v158, v110 offset:28032
	v_add_f32_dpp v2, v2, v2 row_ror:8 row_mask:0xf bank_mask:0xf bound_ctrl:1
	v_pk_mul_f32 v[222:223], v[216:217], v[216:217]
	v_fmac_f32_e32 v224, v6, v220
	s_waitcnt lgkmcnt(7)
	v_pk_fma_f32 v[36:37], v[192:193], v[2:3], v[40:41] op_sel_hi:[1,0,1]
	v_pk_fma_f32 v[38:39], v[194:195], v[2:3], v[42:43] op_sel_hi:[1,0,1]
	v_mul_f32_e32 v44, v36, v136
	v_mul_f32_e32 v59, v204, v36
	v_fmac_f32_e32 v44, v37, v137
	v_fmac_f32_e32 v59, v37, v205
	v_fmac_f32_e32 v44, v38, v138
	v_fmac_f32_e32 v59, v38, v206
	v_fmac_f32_e32 v44, v39, v139
	v_fmac_f32_e32 v59, v39, v207
	v_pk_mul_f32 v[40:41], v[148:149], v[156:157] op_sel_hi:[1,0]
	v_pk_mul_f32 v[42:43], v[150:151], v[156:157] op_sel_hi:[1,0]
	v_add_f32_dpp v2, v44, v44 quad_perm:[1,0,3,2] row_mask:0xf bank_mask:0xf bound_ctrl:1
	v_pk_fma_f32 v[40:41], v[36:37], v[144:145], v[40:41]
	v_pk_fma_f32 v[42:43], v[38:39], v[146:147], v[42:43]
	v_add_f32_dpp v2, v2, v2 quad_perm:[2,3,0,1] row_mask:0xf bank_mask:0xf bound_ctrl:1
	v_add_f32_e32 v228, v222, v228
	v_add_f32_e32 v228, v223, v228
	ds_read_b128 v[188:191], v124 offset:28160
	ds_read_b128 v[192:195], v124 offset:28416
	ds_read_b128 v[196:199], v124 offset:28672
	v_add_f32_dpp v2, v2, v2 row_ror:4 row_mask:0xf bank_mask:0xf bound_ctrl:1
	ds_read_b128 v[200:203], v124 offset:28928
	ds_read_b128 v[204:207], v124 offset:29184
	ds_read_b32 v208, v110 offset:29440
	v_add_f32_dpp v2, v2, v2 row_ror:8 row_mask:0xf bank_mask:0xf bound_ctrl:1
	v_cndmask_b32_e64 v56, v54, v59, s[8:9]
	v_cndmask_b32_e64 v57, v59, v54, s[8:9]
	v_fmac_f32_e32 v224, v7, v221
	v_mov_b32_e32 v220, 0
	s_waitcnt lgkmcnt(6)
; #define LAS __attribute__((address_space(3)))
; __device__ __forceinline__ float row16_sum(float x) { x += dpp_mov<0xB1>(x); x += dpp_mov<0x4E>(x); x += dpp_mov<0x124>(x); x += dpp_mov<0x128>(x); return x; }
; __device__ __forceinline__ void scan_stage(const u32x2 (&pz)[8], LAS float* buf, float* RKB, size_t mrow0, int t0, int tid, int h, int half, ...
;     ...
;     for (int e = 0; e < 4; ++e) { r[e] = zr[e] + (zrp[e] - zr[e]) * mu_r[e]; const float k = zk[e] + (zkp[e] - zk[e]) * mu_k[e]; v[e] = zv[e] + (zvp[e] - zv[e]) * mu_v[e];
;         kkv[e] = k * kkc[e]; n2 += kkv[e] * kkv[e]; k2[e] = k * (1.0f + (ic[e] - 1.0f) * kac[e]); w[e] = __builtin_amdgcn_exp2f(-1.4426950408889634f * ew[e]); rkb += r[e] * k2[e] * rkc[e]; }
;     n2 = row16_sum(n2); rkb = row16_sum(rkb);
;     const float inv = __builtin_amdgcn_rsqf(fmaxf(n2, 1e-24f));
; __device__ __forceinline__ void scan_phase(const KAS Args& a, LAS unsigned char* lds, int i, const int tid_, const int bid, const int nblk) {
;     ...
;                 for (int t = 0; t < TC; ++t) {
;                     f32x4 kk4n = kk4, nb4n = nb4, w4n = w4, k4n = k4, r4n = r4; float vn = v;
;                     if (t + 1 < TC) { const LAS float* sn = sb + (t + 1) * SST;
;                         kk4n = *(const LAS f32x4*)(sn); nb4n = *(const LAS f32x4*)(sn + 64); w4n = *(const LAS f32x4*)(sn + 128); k4n = *(const LAS f32x4*)(sn + 192); r4n = *(const LAS f32x4*)(sn + 256); vn = vb[(t + 1) * SST]; }
;                     __builtin_amdgcn_sched_barrier(0x6);
;                     float sa = fmaf(S[3], kk4[3], fmaf(S[2], kk4[2], fmaf(S[1], kk4[1], S[0] * kk4[0])));
;                     const f32x4 Tm = S * w4 + k4 * v;
;                     sa = row16_sum(sa);
;                     S = Tm + nb4 * sa;
;                     float y = fmaf(S[3], r4[3], fmaf(S[2], r4[2], fmaf(S[1], r4[1], S[0] * r4[0]))); y = row16_sum(y);
;                     ysel = (cgp == (t & 15)) ? y : ysel;
;                     if ((t & 15) == 15) yb[(t - 15 + cgp) * 32 + rl] = ysel;
;                     kk4 = kk4n; nb4 = nb4n; w4 = w4n; k4 = k4n; r4 = r4n; v = vn; }
	v_pk_fma_f32 v[36:37], v[140:141], v[2:3], v[40:41] op_sel_hi:[1,0,1]
	v_pk_fma_f32 v[38:39], v[142:143], v[2:3], v[42:43] op_sel_hi:[1,0,1]
	v_add_f32_dpp v51, v57, v56 quad_perm:[1,0,3,2] row_mask:0xf bank_mask:0xf bound_ctrl:1
	v_mul_f32_e32 v44, v36, v160
	v_mul_f32_e32 v60, v152, v36
	v_fmac_f32_e32 v44, v37, v161
	v_fmac_f32_e32 v60, v37, v153
	v_fmac_f32_e32 v44, v38, v162
	v_fmac_f32_e32 v60, v38, v154
	v_fmac_f32_e32 v44, v39, v163
	v_fmac_f32_e32 v60, v39, v155
	v_pk_mul_f32 v[40:41], v[172:173], v[158:159] op_sel_hi:[1,0]
	v_pk_mul_f32 v[42:43], v[174:175], v[158:159] op_sel_hi:[1,0]
	v_add_f32_dpp v2, v44, v44 quad_perm:[1,0,3,2] row_mask:0xf bank_mask:0xf bound_ctrl:1
	v_pk_fma_f32 v[40:41], v[36:37], v[168:169], v[40:41]
	v_pk_fma_f32 v[42:43], v[38:39], v[170:171], v[42:43]
	v_add_f32_dpp v2, v2, v2 quad_perm:[2,3,0,1] row_mask:0xf bank_mask:0xf bound_ctrl:1
	v_add_f32_dpp v228, v228, v228 quad_perm:[1,0,3,2] row_mask:0xf bank_mask:0xf bound_ctrl:1
	v_add_f32_dpp v219, v224, v224 quad_perm:[1,0,3,2] row_mask:0xf bank_mask:0xf bound_ctrl:1
	ds_read_b128 v[136:139], v124 offset:29568
	ds_read_b128 v[140:143], v124 offset:29824
	ds_read_b128 v[144:147], v124 offset:30080
	v_add_f32_dpp v2, v2, v2 row_ror:4 row_mask:0xf bank_mask:0xf bound_ctrl:1
	ds_read_b128 v[148:151], v124 offset:30336
	ds_read_b128 v[152:155], v124 offset:30592
	ds_read_b32 v156, v110 offset:30848
	v_add_f32_dpp v2, v2, v2 row_ror:8 row_mask:0xf bank_mask:0xf bound_ctrl:1
	v_add_f32_dpp v228, v228, v228 quad_perm:[2,3,0,1] row_mask:0xf bank_mask:0xf bound_ctrl:1
	v_add_f32_dpp v219, v219, v219 quad_perm:[2,3,0,1] row_mask:0xf bank_mask:0xf bound_ctrl:1
	s_waitcnt lgkmcnt(6)
	v_pk_fma_f32 v[36:37], v[164:165], v[2:3], v[40:41] op_sel_hi:[1,0,1]
	v_pk_fma_f32 v[38:39], v[166:167], v[2:3], v[42:43] op_sel_hi:[1,0,1]
	v_mul_f32_e32 v44, v36, v188
	v_mul_f32_e32 v62, v176, v36
	v_fmac_f32_e32 v44, v37, v189
	v_fmac_f32_e32 v62, v37, v177
	v_fmac_f32_e32 v44, v38, v190
	v_fmac_f32_e32 v62, v38, v178
	v_fmac_f32_e32 v44, v39, v191
	v_fmac_f32_e32 v62, v39, v179
	v_pk_mul_f32 v[40:41], v[200:201], v[208:209] op_sel_hi:[1,0]
	v_pk_mul_f32 v[42:43], v[202:203], v[208:209] op_sel_hi:[1,0]
	v_add_f32_dpp v2, v44, v44 quad_perm:[1,0,3,2] row_mask:0xf bank_mask:0xf bound_ctrl:1
	v_pk_fma_f32 v[40:41], v[36:37], v[196:197], v[40:41]
	v_pk_fma_f32 v[42:43], v[38:39], v[198:199], v[42:43]
	v_add_f32_dpp v2, v2, v2 quad_perm:[2,3,0,1] row_mask:0xf bank_mask:0xf bound_ctrl:1
	v_add_f32_dpp v228, v228, v228 row_ror:4 row_mask:0xf bank_mask:0xf bound_ctrl:1
	v_add_f32_dpp v219, v219, v219 row_ror:4 row_mask:0xf bank_mask:0xf bound_ctrl:1
	ds_read_b128 v[160:163], v124 offset:30976
	ds_read_b128 v[164:167], v124 offset:31232
	ds_read_b128 v[168:171], v124 offset:31488
	v_add_f32_dpp v2, v2, v2 row_ror:4 row_mask:0xf bank_mask:0xf bound_ctrl:1
	ds_read_b128 v[172:175], v124 offset:31744
	ds_read_b128 v[176:179], v124 offset:32000
	ds_read_b32 v158, v110 offset:32256
	v_add_f32_dpp v2, v2, v2 row_ror:8 row_mask:0xf bank_mask:0xf bound_ctrl:1
	v_cndmask_b32_e64 v56, v60, v62, s[8:9]
	v_cndmask_b32_e64 v57, v62, v60, s[8:9]
	v_mov_b32_dpp v218, v228 row_ror:8 row_mask:0xf bank_mask:0xf
	v_mov_b32_dpp v220, v219 row_ror:8 row_mask:0xf bank_mask:0xf
	s_waitcnt lgkmcnt(6)
	v_pk_fma_f32 v[36:37], v[192:193], v[2:3], v[40:41] op_sel_hi:[1,0,1]
	v_pk_fma_f32 v[38:39], v[194:195], v[2:3], v[42:43] op_sel_hi:[1,0,1]
	v_add_f32_dpp v63, v57, v56 quad_perm:[1,0,3,2] row_mask:0xf bank_mask:0xf bound_ctrl:1
	v_cndmask_b32_e64 v56, v51, v63, s[10:11]
	v_cndmask_b32_e64 v57, v63, v51, s[10:11]
	v_mul_f32_e32 v44, v36, v136
	v_mul_f32_e32 v66, v204, v36
	v_add_f32_dpp v65, v57, v56 quad_perm:[2,3,0,1] row_mask:0xf bank_mask:0xf bound_ctrl:1
	v_fmac_f32_e32 v44, v37, v137
	v_fmac_f32_e32 v66, v37, v205
	v_fmac_f32_e32 v44, v38, v138
	v_fmac_f32_e32 v66, v38, v206
	v_fmac_f32_e32 v44, v39, v139
	v_fmac_f32_e32 v66, v39, v207
	v_pk_mul_f32 v[40:41], v[148:149], v[156:157] op_sel_hi:[1,0]
	v_pk_mul_f32 v[42:43], v[150:151], v[156:157] op_sel_hi:[1,0]
	v_add_f32_dpp v2, v44, v44 quad_perm:[1,0,3,2] row_mask:0xf bank_mask:0xf bound_ctrl:1
	v_pk_fma_f32 v[40:41], v[36:37], v[144:145], v[40:41]
	v_pk_fma_f32 v[42:43], v[38:39], v[146:147], v[42:43]
	v_add_f32_dpp v2, v2, v2 quad_perm:[2,3,0,1] row_mask:0xf bank_mask:0xf bound_ctrl:1
	v_add_f32_e32 v245, v219, v220
	v_add_f32_e32 v228, v228, v218
	ds_read_b128 v[188:191], v124 offset:32384
	ds_read_b128 v[192:195], v124 offset:32640
	ds_read_b128 v[196:199], v124 offset:32896
	v_add_f32_dpp v2, v2, v2 row_ror:4 row_mask:0xf bank_mask:0xf bound_ctrl:1
	ds_read_b128 v[200:203], v124 offset:33152
	ds_read_b128 v[204:207], v124 offset:33408
	ds_read_b32 v208, v110 offset:33664
	v_add_f32_dpp v2, v2, v2 row_ror:8 row_mask:0xf bank_mask:0xf bound_ctrl:1
	v_max_f32_e32 v228, 0x179abe15, v228
	v_lshlrev_b32_e32 v219, 16, v92
	s_waitcnt lgkmcnt(6)
; #define LAS __attribute__((address_space(3)))
; __device__ __forceinline__ void scan_stage(const u32x2 (&pz)[8], LAS float* buf, float* RKB, size_t mrow0, int t0, int tid, int h, int half, ...
;     ...
;     for (int e = 0; e < 4; ++e) { r[e] = zr[e] + (zrp[e] - zr[e]) * mu_r[e]; const float k = zk[e] + (zkp[e] - zk[e]) * mu_k[e]; v[e] = zv[e] + (zvp[e] - zv[e]) * mu_v[e];
;         kkv[e] = k * kkc[e]; n2 += kkv[e] * kkv[e]; k2[e] = k * (1.0f + (ic[e] - 1.0f) * kac[e]); w[e] = __builtin_amdgcn_exp2f(-1.4426950408889634f * ew[e]); rkb += r[e] * k2[e] * rkc[e]; }
;     n2 = row16_sum(n2); rkb = row16_sum(rkb);
;     const float inv = __builtin_amdgcn_rsqf(fmaxf(n2, 1e-24f));
;     const f32x4 kkn = kkv * inv; f32x4 nb;
; #pragma unroll
;     for (int e = 0; e < 4; ++e) nb[e] = -kkn[e] * ic[e];
;     if (half == 0 && cgp == 0) RKB[(mrow0 + t0 + tl) * 8 + h] = rkb;
;     LAS float* sb = buf + tl * SST + 4 * cgp;
;     *(LAS f32x4*)(sb) = kkn; *(LAS f32x4*)(sb + 64) = nb; *(LAS f32x4*)(sb + 128) = w; *(LAS f32x4*)(sb + 192) = k2; *(LAS f32x4*)(sb + 256) = r;
; __device__ __forceinline__ void scan_phase(const KAS Args& a, LAS unsigned char* lds, int i, const int tid_, const int bid, const int nblk) {
;     ...
;                 for (int t = 0; t < TC; ++t) {
;                     f32x4 kk4n = kk4, nb4n = nb4, w4n = w4, k4n = k4, r4n = r4; float vn = v;
;                     if (t + 1 < TC) { const LAS float* sn = sb + (t + 1) * SST;
;                         kk4n = *(const LAS f32x4*)(sn); nb4n = *(const LAS f32x4*)(sn + 64); w4n = *(const LAS f32x4*)(sn + 128); k4n = *(const LAS f32x4*)(sn + 192); r4n = *(const LAS f32x4*)(sn + 256); vn = vb[(t + 1) * SST]; }
;                     __builtin_amdgcn_sched_barrier(0x6);
;                     float sa = fmaf(S[3], kk4[3], fmaf(S[2], kk4[2], fmaf(S[1], kk4[1], S[0] * kk4[0])));
;                     const f32x4 Tm = S * w4 + k4 * v;
;                     sa = row16_sum(sa);
;                     S = Tm + nb4 * sa;
;                     float y = fmaf(S[3], r4[3], fmaf(S[2], r4[2], fmaf(S[1], r4[1], S[0] * r4[0]))); y = row16_sum(y);
;                     ysel = (cgp == (t & 15)) ? y : ysel;
;                     if ((t & 15) == 15) yb[(t - 15 + cgp) * 32 + rl] = ysel;
;                     kk4 = kk4n; nb4 = nb4n; w4 = w4n; k4 = k4n; r4 = r4n; v = vn; }
	v_pk_fma_f32 v[36:37], v[140:141], v[2:3], v[40:41] op_sel_hi:[1,0,1]
	v_pk_fma_f32 v[38:39], v[142:143], v[2:3], v[42:43] op_sel_hi:[1,0,1]
	v_mul_f32_e32 v44, v36, v160
	v_mul_f32_e32 v64, v152, v36
	v_fmac_f32_e32 v44, v37, v161
	v_fmac_f32_e32 v64, v37, v153
	v_fmac_f32_e32 v44, v38, v162
	v_fmac_f32_e32 v64, v38, v154
	v_fmac_f32_e32 v44, v39, v163
	v_fmac_f32_e32 v64, v39, v155
	v_pk_mul_f32 v[40:41], v[172:173], v[158:159] op_sel_hi:[1,0]
	v_pk_mul_f32 v[42:43], v[174:175], v[158:159] op_sel_hi:[1,0]
	v_add_f32_dpp v2, v44, v44 quad_perm:[1,0,3,2] row_mask:0xf bank_mask:0xf bound_ctrl:1
	v_pk_fma_f32 v[40:41], v[36:37], v[168:169], v[40:41]
	v_pk_fma_f32 v[42:43], v[38:39], v[170:171], v[42:43]
	v_add_f32_dpp v2, v2, v2 quad_perm:[2,3,0,1] row_mask:0xf bank_mask:0xf bound_ctrl:1
	v_rsq_f32_e32 v228, v228
	v_and_b32_e32 v221, 0xffff0000, v92
	ds_read_b128 v[136:139], v124 offset:33792
	ds_read_b128 v[140:143], v124 offset:34048
	ds_read_b128 v[144:147], v124 offset:34304
	v_add_f32_dpp v2, v2, v2 row_ror:4 row_mask:0xf bank_mask:0xf bound_ctrl:1
	ds_read_b128 v[148:151], v124 offset:34560
	ds_read_b128 v[152:155], v124 offset:34816
	ds_read_b32 v156, v110 offset:35072
	v_add_f32_dpp v2, v2, v2 row_ror:8 row_mask:0xf bank_mask:0xf bound_ctrl:1
	v_cndmask_b32_e64 v56, v66, v64, s[8:9]
	v_cndmask_b32_e64 v57, v64, v66, s[8:9]
	v_mul_f32_e32 v219, 0xbfb8aa3b, v219
	s_bitcmp1_b32 s62, 0
	s_cselect_b32 s2, 0xb000, 0
	s_waitcnt lgkmcnt(6)
	v_pk_fma_f32 v[36:37], v[164:165], v[2:3], v[40:41] op_sel_hi:[1,0,1]
	v_pk_fma_f32 v[38:39], v[166:167], v[2:3], v[42:43] op_sel_hi:[1,0,1]
	v_add_f32_dpp v67, v57, v56 quad_perm:[1,0,3,2] row_mask:0xf bank_mask:0xf bound_ctrl:1
	v_mul_f32_e32 v44, v36, v188
	v_mul_f32_e32 v46, v176, v36
	v_fmac_f32_e32 v44, v37, v189
	v_fmac_f32_e32 v46, v37, v177
	v_fmac_f32_e32 v44, v38, v190
	v_fmac_f32_e32 v46, v38, v178
	v_fmac_f32_e32 v44, v39, v191
	v_fmac_f32_e32 v46, v39, v179
	v_pk_mul_f32 v[40:41], v[200:201], v[208:209] op_sel_hi:[1,0]
	v_pk_mul_f32 v[42:43], v[202:203], v[208:209] op_sel_hi:[1,0]
	v_add_f32_dpp v2, v44, v44 quad_perm:[1,0,3,2] row_mask:0xf bank_mask:0xf bound_ctrl:1
	v_pk_fma_f32 v[40:41], v[36:37], v[196:197], v[40:41]
	v_pk_fma_f32 v[42:43], v[38:39], v[198:199], v[42:43]
	v_add_f32_dpp v2, v2, v2 quad_perm:[2,3,0,1] row_mask:0xf bank_mask:0xf bound_ctrl:1
	v_lshlrev_b32_e32 v222, 16, v93
	v_and_b32_e32 v223, 0xffff0000, v93
	ds_read_b128 v[160:163], v124 offset:35200
	ds_read_b128 v[164:167], v124 offset:35456
	ds_read_b128 v[168:171], v124 offset:35712
	v_add_f32_dpp v2, v2, v2 row_ror:4 row_mask:0xf bank_mask:0xf bound_ctrl:1
	ds_read_b128 v[172:175], v124 offset:35968
	ds_read_b128 v[176:179], v124 offset:36224
	ds_read_b32 v158, v110 offset:36480
	v_add_f32_dpp v2, v2, v2 row_ror:8 row_mask:0xf bank_mask:0xf bound_ctrl:1
	v_exp_f32_e32 v220, v219
	v_mul_f32_e32 v219, 0xbfb8aa3b, v221
	s_waitcnt lgkmcnt(6)
	v_pk_fma_f32 v[36:37], v[192:193], v[2:3], v[40:41] op_sel_hi:[1,0,1]
	v_pk_fma_f32 v[38:39], v[194:195], v[2:3], v[42:43] op_sel_hi:[1,0,1]
	v_mul_f32_e32 v44, v36, v136
	v_mul_f32_e32 v48, v204, v36
	v_fmac_f32_e32 v44, v37, v137
	v_fmac_f32_e32 v48, v37, v205
	v_fmac_f32_e32 v44, v38, v138
	v_fmac_f32_e32 v48, v38, v206
	v_fmac_f32_e32 v44, v39, v139
	v_fmac_f32_e32 v48, v39, v207
	v_pk_mul_f32 v[40:41], v[148:149], v[156:157] op_sel_hi:[1,0]
	v_pk_mul_f32 v[42:43], v[150:151], v[156:157] op_sel_hi:[1,0]
	v_add_f32_dpp v2, v44, v44 quad_perm:[1,0,3,2] row_mask:0xf bank_mask:0xf bound_ctrl:1
	v_pk_fma_f32 v[40:41], v[36:37], v[144:145], v[40:41]
	v_pk_fma_f32 v[42:43], v[38:39], v[146:147], v[42:43]
	v_add_f32_dpp v2, v2, v2 quad_perm:[2,3,0,1] row_mask:0xf bank_mask:0xf bound_ctrl:1
	v_exp_f32_e32 v221, v219
	v_mul_f32_e32 v219, 0xbfb8aa3b, v222
	ds_read_b128 v[188:191], v124 offset:36608
	ds_read_b128 v[192:195], v124 offset:36864
	ds_read_b128 v[196:199], v124 offset:37120
	v_add_f32_dpp v2, v2, v2 row_ror:4 row_mask:0xf bank_mask:0xf bound_ctrl:1
	ds_read_b128 v[200:203], v124 offset:37376
	ds_read_b128 v[204:207], v124 offset:37632
	ds_read_b32 v208, v110 offset:37888
	v_add_f32_dpp v2, v2, v2 row_ror:8 row_mask:0xf bank_mask:0xf bound_ctrl:1
	v_cndmask_b32_e64 v56, v46, v48, s[8:9]
	v_cndmask_b32_e64 v57, v48, v46, s[8:9]
	v_mul_f32_e32 v218, 0xbfb8aa3b, v223
	v_exp_f32_e32 v222, v219
	s_waitcnt lgkmcnt(6)
	v_pk_fma_f32 v[36:37], v[140:141], v[2:3], v[40:41] op_sel_hi:[1,0,1]
	v_pk_fma_f32 v[38:39], v[142:143], v[2:3], v[42:43] op_sel_hi:[1,0,1]
	v_add_f32_dpp v47, v57, v56 quad_perm:[1,0,3,2] row_mask:0xf bank_mask:0xf bound_ctrl:1
	v_cndmask_b32_e64 v56, v67, v47, s[10:11]
	v_cndmask_b32_e64 v57, v47, v67, s[10:11]
	v_mul_f32_e32 v44, v36, v160
	v_mul_f32_e32 v52, v152, v36
	v_add_f32_dpp v50, v57, v56 quad_perm:[2,3,0,1] row_mask:0xf bank_mask:0xf bound_ctrl:1
	v_fmac_f32_e32 v44, v37, v161
	v_fmac_f32_e32 v52, v37, v153
	v_add_f32_dpp v49, v65, v65 row_shl:4 row_mask:0xf bank_mask:0x5
	v_fmac_f32_e32 v44, v38, v162
	v_fmac_f32_e32 v52, v38, v154
	v_add_f32_dpp v49, v50, v50 row_shr:4 row_mask:0xf bank_mask:0xa
	v_fmac_f32_e32 v44, v39, v163
	v_fmac_f32_e32 v52, v39, v155
	v_pk_mul_f32 v[40:41], v[172:173], v[158:159] op_sel_hi:[1,0]
	v_pk_mul_f32 v[42:43], v[174:175], v[158:159] op_sel_hi:[1,0]
	v_add_f32_dpp v2, v44, v44 quad_perm:[1,0,3,2] row_mask:0xf bank_mask:0xf bound_ctrl:1
	v_pk_fma_f32 v[40:41], v[36:37], v[168:169], v[40:41]
	v_pk_fma_f32 v[42:43], v[38:39], v[170:171], v[42:43]
	v_add_f32_dpp v2, v2, v2 quad_perm:[2,3,0,1] row_mask:0xf bank_mask:0xf bound_ctrl:1
	v_exp_f32_e32 v223, v218
	v_pk_mul_f32 v[224:225], v[212:213], v[228:229] op_sel_hi:[1,0]
	ds_read_b128 v[136:139], v124 offset:38016
	ds_read_b128 v[140:143], v124 offset:38272
	ds_read_b128 v[144:147], v124 offset:38528
	v_add_f32_dpp v2, v2, v2 row_ror:4 row_mask:0xf bank_mask:0xf bound_ctrl:1
	ds_read_b128 v[148:151], v124 offset:38784
	ds_read_b128 v[152:155], v124 offset:39040
	ds_read_b32 v156, v110 offset:39296
	v_add_f32_dpp v2, v2, v2 row_ror:8 row_mask:0xf bank_mask:0xf bound_ctrl:1
	v_pk_mul_f32 v[226:227], v[216:217], v[228:229] op_sel_hi:[1,0]
	v_add_u32_e32 v228, s2, v113
	s_waitcnt lgkmcnt(6)
; #define LAS __attribute__((address_space(3)))
; __device__ __forceinline__ float row16_sum(float x) { x += dpp_mov<0xB1>(x); x += dpp_mov<0x4E>(x); x += dpp_mov<0x124>(x); x += dpp_mov<0x128>(x); return x; }
; __device__ __forceinline__ void scan_stage(const u32x2 (&pz)[8], LAS float* buf, float* RKB, size_t mrow0, int t0, int tid, int h, int half, ...
;     ...
;     const f32x4 kkn = kkv * inv; f32x4 nb;
; #pragma unroll
;     for (int e = 0; e < 4; ++e) nb[e] = -kkn[e] * ic[e];
;     if (half == 0 && cgp == 0) RKB[(mrow0 + t0 + tl) * 8 + h] = rkb;
;     LAS float* sb = buf + tl * SST + 4 * cgp;
;     *(LAS f32x4*)(sb) = kkn; *(LAS f32x4*)(sb + 64) = nb; *(LAS f32x4*)(sb + 128) = w; *(LAS f32x4*)(sb + 192) = k2; *(LAS f32x4*)(sb + 256) = r;
; __device__ __forceinline__ void scan_phase(const KAS Args& a, LAS unsigned char* lds, int i, const int tid_, const int bid, const int nblk) {
;     ...
;                 for (int t = 0; t < TC; ++t) {
;                     f32x4 kk4n = kk4, nb4n = nb4, w4n = w4, k4n = k4, r4n = r4; float vn = v;
;                     if (t + 1 < TC) { const LAS float* sn = sb + (t + 1) * SST;
;                         kk4n = *(const LAS f32x4*)(sn); nb4n = *(const LAS f32x4*)(sn + 64); w4n = *(const LAS f32x4*)(sn + 128); k4n = *(const LAS f32x4*)(sn + 192); r4n = *(const LAS f32x4*)(sn + 256); vn = vb[(t + 1) * SST]; }
;                     __builtin_amdgcn_sched_barrier(0x6);
;                     float sa = fmaf(S[3], kk4[3], fmaf(S[2], kk4[2], fmaf(S[1], kk4[1], S[0] * kk4[0])));
;                     const f32x4 Tm = S * w4 + k4 * v;
;                     sa = row16_sum(sa);
;                     S = Tm + nb4 * sa;
;                     float y = fmaf(S[3], r4[3], fmaf(S[2], r4[2], fmaf(S[1], r4[1], S[0] * r4[0]))); y = row16_sum(y);
;                     ysel = (cgp == (t & 15)) ? y : ysel;
;                     if ((t & 15) == 15) yb[(t - 15 + cgp) * 32 + rl] = ysel;
;                     kk4 = kk4n; nb4 = nb4n; w4 = w4n; k4 = k4n; r4 = r4n; v = vn; }
	v_pk_fma_f32 v[36:37], v[164:165], v[2:3], v[40:41] op_sel_hi:[1,0,1]
	v_pk_fma_f32 v[38:39], v[166:167], v[2:3], v[42:43] op_sel_hi:[1,0,1]
	v_mul_f32_e32 v44, v36, v188
	v_mul_f32_e32 v45, v176, v36
	v_fmac_f32_e32 v44, v37, v189
	v_fmac_f32_e32 v45, v37, v177
	v_fmac_f32_e32 v44, v38, v190
	v_fmac_f32_e32 v45, v38, v178
	v_fmac_f32_e32 v44, v39, v191
	v_fmac_f32_e32 v45, v39, v179
	v_pk_mul_f32 v[40:41], v[200:201], v[208:209] op_sel_hi:[1,0]
	v_pk_mul_f32 v[42:43], v[202:203], v[208:209] op_sel_hi:[1,0]
	v_add_f32_dpp v2, v44, v44 quad_perm:[1,0,3,2] row_mask:0xf bank_mask:0xf bound_ctrl:1
	v_pk_fma_f32 v[40:41], v[36:37], v[196:197], v[40:41]
	v_pk_fma_f32 v[42:43], v[38:39], v[198:199], v[42:43]
	v_add_f32_dpp v2, v2, v2 quad_perm:[2,3,0,1] row_mask:0xf bank_mask:0xf bound_ctrl:1
	v_pk_mul_f32 v[212:213], v[214:215], v[226:227] neg_lo:[0,1] neg_hi:[0,1]
	v_add_u32_e32 v214, v228, v114
	ds_read_b128 v[160:163], v124 offset:39424
	ds_read_b128 v[164:167], v124 offset:39680
	ds_read_b128 v[168:171], v124 offset:39936
	v_add_f32_dpp v2, v2, v2 row_ror:4 row_mask:0xf bank_mask:0xf bound_ctrl:1
	ds_read_b128 v[172:175], v124 offset:40192
	ds_read_b128 v[176:179], v124 offset:40448
	ds_read_b32 v158, v110 offset:40704
	v_add_f32_dpp v2, v2, v2 row_ror:8 row_mask:0xf bank_mask:0xf bound_ctrl:1
	v_cndmask_b32_e64 v56, v52, v45, s[8:9]
	v_cndmask_b32_e64 v57, v45, v52, s[8:9]
	v_pk_mul_f32 v[210:211], v[210:211], v[224:225] neg_lo:[0,1] neg_hi:[0,1]
	ds_write_b128 v214, v[224:227]
	s_waitcnt lgkmcnt(7)
	v_pk_fma_f32 v[36:37], v[192:193], v[2:3], v[40:41] op_sel_hi:[1,0,1]
	v_pk_fma_f32 v[38:39], v[194:195], v[2:3], v[42:43] op_sel_hi:[1,0,1]
	v_add_f32_dpp v53, v57, v56 quad_perm:[1,0,3,2] row_mask:0xf bank_mask:0xf bound_ctrl:1
	v_mul_f32_e32 v44, v36, v136
	v_mul_f32_e32 v61, v204, v36
	v_fmac_f32_e32 v44, v37, v137
	v_fmac_f32_e32 v61, v37, v205
	v_fmac_f32_e32 v44, v38, v138
	v_fmac_f32_e32 v61, v38, v206
	v_fmac_f32_e32 v44, v39, v139
	v_fmac_f32_e32 v61, v39, v207
	v_pk_mul_f32 v[40:41], v[148:149], v[156:157] op_sel_hi:[1,0]
	v_pk_mul_f32 v[42:43], v[150:151], v[156:157] op_sel_hi:[1,0]
	v_add_f32_dpp v2, v44, v44 quad_perm:[1,0,3,2] row_mask:0xf bank_mask:0xf bound_ctrl:1
	v_pk_fma_f32 v[40:41], v[36:37], v[144:145], v[40:41]
	v_pk_fma_f32 v[42:43], v[38:39], v[146:147], v[42:43]
	v_add_f32_dpp v2, v2, v2 quad_perm:[2,3,0,1] row_mask:0xf bank_mask:0xf bound_ctrl:1
	ds_write_b128 v214, v[210:213] offset:256
	ds_write_b128 v214, v[220:223] offset:512
	ds_read_b128 v[188:191], v124 offset:40832
	ds_read_b128 v[192:195], v124 offset:41088
	ds_read_b128 v[196:199], v124 offset:41344
	v_add_f32_dpp v2, v2, v2 row_ror:4 row_mask:0xf bank_mask:0xf bound_ctrl:1
	ds_read_b128 v[200:203], v124 offset:41600
	ds_read_b128 v[204:207], v124 offset:41856
	ds_read_b32 v208, v110 offset:42112
	v_add_f32_dpp v2, v2, v2 row_ror:8 row_mask:0xf bank_mask:0xf bound_ctrl:1
	ds_write_b128 v214, v[32:35] offset:768
	ds_write_b128 v214, v[28:31] offset:1024
	s_waitcnt lgkmcnt(11)
	v_pk_fma_f32 v[36:37], v[140:141], v[2:3], v[40:41] op_sel_hi:[1,0,1]
	v_pk_fma_f32 v[38:39], v[142:143], v[2:3], v[42:43] op_sel_hi:[1,0,1]
	v_mul_f32_e32 v44, v36, v160
	v_mul_f32_e32 v55, v152, v36
	v_fmac_f32_e32 v44, v37, v161
	v_fmac_f32_e32 v55, v37, v153
	v_fmac_f32_e32 v44, v38, v162
	v_fmac_f32_e32 v55, v38, v154
	v_fmac_f32_e32 v44, v39, v163
	v_fmac_f32_e32 v55, v39, v155
	v_pk_mul_f32 v[40:41], v[172:173], v[158:159] op_sel_hi:[1,0]
	v_pk_mul_f32 v[42:43], v[174:175], v[158:159] op_sel_hi:[1,0]
	v_add_f32_dpp v2, v44, v44 quad_perm:[1,0,3,2] row_mask:0xf bank_mask:0xf bound_ctrl:1
	v_pk_fma_f32 v[40:41], v[36:37], v[168:169], v[40:41]
	v_pk_fma_f32 v[42:43], v[38:39], v[170:171], v[42:43]
	v_add_f32_dpp v2, v2, v2 quad_perm:[2,3,0,1] row_mask:0xf bank_mask:0xf bound_ctrl:1
	ds_read_b128 v[136:139], v124 offset:42240
	ds_read_b128 v[140:143], v124 offset:42496
	ds_read_b128 v[144:147], v124 offset:42752
	v_add_f32_dpp v2, v2, v2 row_ror:4 row_mask:0xf bank_mask:0xf bound_ctrl:1
	ds_read_b128 v[148:151], v124 offset:43008
	ds_read_b128 v[152:155], v124 offset:43264
	ds_read_b32 v156, v110 offset:43520
	v_add_f32_dpp v2, v2, v2 row_ror:8 row_mask:0xf bank_mask:0xf bound_ctrl:1
	v_cndmask_b32_e64 v56, v61, v55, s[8:9]
	v_cndmask_b32_e64 v57, v55, v61, s[8:9]
	s_waitcnt lgkmcnt(8)
; #define LAS __attribute__((address_space(3)))
; __device__ __forceinline__ float row16_sum(float x) { x += dpp_mov<0xB1>(x); x += dpp_mov<0x4E>(x); x += dpp_mov<0x124>(x); x += dpp_mov<0x128>(x); return x; }
; __device__ __forceinline__ void scan_stage(const u32x2 (&pz)[8], LAS float* buf, float* RKB, size_t mrow0, int t0, int tid, int h, int half, ...
;     ...
;     if (half == 0 && cgp == 0) RKB[(mrow0 + t0 + tl) * 8 + h] = rkb;
; __device__ __forceinline__ void scan_phase(const KAS Args& a, LAS unsigned char* lds, int i, const int tid_, const int bid, const int nblk) {
;     ...
;                 for (int t = 0; t < TC; ++t) {
;                     f32x4 kk4n = kk4, nb4n = nb4, w4n = w4, k4n = k4, r4n = r4; float vn = v;
;                     if (t + 1 < TC) { const LAS float* sn = sb + (t + 1) * SST;
;                         kk4n = *(const LAS f32x4*)(sn); nb4n = *(const LAS f32x4*)(sn + 64); w4n = *(const LAS f32x4*)(sn + 128); k4n = *(const LAS f32x4*)(sn + 192); r4n = *(const LAS f32x4*)(sn + 256); vn = vb[(t + 1) * SST]; }
;                     __builtin_amdgcn_sched_barrier(0x6);
;                     float sa = fmaf(S[3], kk4[3], fmaf(S[2], kk4[2], fmaf(S[1], kk4[1], S[0] * kk4[0])));
;                     const f32x4 Tm = S * w4 + k4 * v;
;                     sa = row16_sum(sa);
;                     S = Tm + nb4 * sa;
;                     float y = fmaf(S[3], r4[3], fmaf(S[2], r4[2], fmaf(S[1], r4[1], S[0] * r4[0]))); y = row16_sum(y);
;                     ysel = (cgp == (t & 15)) ? y : ysel;
;                     if ((t & 15) == 15) yb[(t - 15 + cgp) * 32 + rl] = ysel;
;                     kk4 = kk4n; nb4 = nb4n; w4 = w4n; k4 = k4n; r4 = r4n; v = vn; }
	v_pk_fma_f32 v[36:37], v[164:165], v[2:3], v[40:41] op_sel_hi:[1,0,1]
	v_pk_fma_f32 v[38:39], v[166:167], v[2:3], v[42:43] op_sel_hi:[1,0,1]
	v_add_f32_dpp v58, v57, v56 quad_perm:[1,0,3,2] row_mask:0xf bank_mask:0xf bound_ctrl:1
	v_cndmask_b32_e64 v56, v53, v58, s[10:11]
	v_cndmask_b32_e64 v57, v58, v53, s[10:11]
	v_mul_f32_e32 v44, v36, v188
	v_mul_f32_e32 v59, v176, v36
	v_add_f32_dpp v54, v57, v56 quad_perm:[2,3,0,1] row_mask:0xf bank_mask:0xf bound_ctrl:1
	v_fmac_f32_e32 v44, v37, v189
	v_fmac_f32_e32 v59, v37, v177
	v_fmac_f32_e32 v44, v38, v190
	v_fmac_f32_e32 v59, v38, v178
	v_fmac_f32_e32 v44, v39, v191
	v_fmac_f32_e32 v59, v39, v179
	v_pk_mul_f32 v[40:41], v[200:201], v[208:209] op_sel_hi:[1,0]
	v_pk_mul_f32 v[42:43], v[202:203], v[208:209] op_sel_hi:[1,0]
	v_add_f32_dpp v2, v44, v44 quad_perm:[1,0,3,2] row_mask:0xf bank_mask:0xf bound_ctrl:1
	v_pk_fma_f32 v[40:41], v[36:37], v[196:197], v[40:41]
	v_pk_fma_f32 v[42:43], v[38:39], v[198:199], v[42:43]
	v_add_f32_dpp v2, v2, v2 quad_perm:[2,3,0,1] row_mask:0xf bank_mask:0xf bound_ctrl:1
	ds_read_b128 v[160:163], v124 offset:43648
	ds_read_b128 v[164:167], v124 offset:43904
	ds_read_b128 v[168:171], v124 offset:44160
	v_add_f32_dpp v2, v2, v2 row_ror:4 row_mask:0xf bank_mask:0xf bound_ctrl:1
	ds_read_b128 v[172:175], v124 offset:44416
	ds_read_b128 v[176:179], v124 offset:44672
	ds_read_b32 v158, v110 offset:44928
	v_add_f32_dpp v2, v2, v2 row_ror:8 row_mask:0xf bank_mask:0xf bound_ctrl:1
	s_waitcnt lgkmcnt(6)
	v_pk_fma_f32 v[36:37], v[192:193], v[2:3], v[40:41] op_sel_hi:[1,0,1]
	v_pk_fma_f32 v[38:39], v[194:195], v[2:3], v[42:43] op_sel_hi:[1,0,1]
	v_mul_f32_e32 v44, v36, v136
	v_mul_f32_e32 v60, v204, v36
	v_fmac_f32_e32 v44, v37, v137
	v_fmac_f32_e32 v60, v37, v205
	v_fmac_f32_e32 v44, v38, v138
	v_fmac_f32_e32 v60, v38, v206
	v_fmac_f32_e32 v44, v39, v139
	v_fmac_f32_e32 v60, v39, v207
	v_pk_mul_f32 v[40:41], v[148:149], v[156:157] op_sel_hi:[1,0]
	v_pk_mul_f32 v[42:43], v[150:151], v[156:157] op_sel_hi:[1,0]
	v_add_f32_dpp v2, v44, v44 quad_perm:[1,0,3,2] row_mask:0xf bank_mask:0xf bound_ctrl:1
	v_pk_fma_f32 v[40:41], v[36:37], v[144:145], v[40:41]
	v_pk_fma_f32 v[42:43], v[38:39], v[146:147], v[42:43]
	v_add_f32_dpp v2, v2, v2 quad_perm:[2,3,0,1] row_mask:0xf bank_mask:0xf bound_ctrl:1
	v_cndmask_b32_e64 v56, v59, v60, s[8:9]
	v_cndmask_b32_e64 v57, v60, v59, s[8:9]
	v_add_f32_dpp v2, v2, v2 row_ror:4 row_mask:0xf bank_mask:0xf bound_ctrl:1
	s_nop 0
	v_add_f32_dpp v62, v57, v56 quad_perm:[1,0,3,2] row_mask:0xf bank_mask:0xf bound_ctrl:1
	v_add_f32_dpp v2, v2, v2 row_ror:8 row_mask:0xf bank_mask:0xf bound_ctrl:1
	s_waitcnt lgkmcnt(0)
	v_pk_fma_f32 v[36:37], v[140:141], v[2:3], v[40:41] op_sel_hi:[1,0,1]
	v_pk_fma_f32 v[38:39], v[142:143], v[2:3], v[42:43] op_sel_hi:[1,0,1]
	v_mul_f32_e32 v44, v36, v160
	v_mul_f32_e32 v51, v152, v36
	v_fmac_f32_e32 v44, v37, v161
	v_fmac_f32_e32 v51, v37, v153
	v_fmac_f32_e32 v44, v38, v162
	v_fmac_f32_e32 v51, v38, v154
	v_fmac_f32_e32 v44, v39, v163
	v_fmac_f32_e32 v51, v39, v155
	v_pk_mul_f32 v[40:41], v[172:173], v[158:159] op_sel_hi:[1,0]
	v_pk_mul_f32 v[42:43], v[174:175], v[158:159] op_sel_hi:[1,0]
	v_add_f32_dpp v2, v44, v44 quad_perm:[1,0,3,2] row_mask:0xf bank_mask:0xf bound_ctrl:1
	v_pk_fma_f32 v[40:41], v[36:37], v[168:169], v[40:41]
	v_pk_fma_f32 v[42:43], v[38:39], v[170:171], v[42:43]
	v_add_f32_dpp v2, v2, v2 quad_perm:[2,3,0,1] row_mask:0xf bank_mask:0xf bound_ctrl:1
	s_nop 0
	s_nop 0
	v_add_f32_dpp v2, v2, v2 row_ror:4 row_mask:0xf bank_mask:0xf bound_ctrl:1
	s_nop 0
	s_nop 0
	v_add_f32_dpp v2, v2, v2 row_ror:8 row_mask:0xf bank_mask:0xf bound_ctrl:1
	v_pk_fma_f32 v[36:37], v[164:165], v[2:3], v[40:41] op_sel_hi:[1,0,1]
	v_pk_fma_f32 v[38:39], v[166:167], v[2:3], v[42:43] op_sel_hi:[1,0,1]
	v_mul_f32_e32 v63, v176, v36
	v_fmac_f32_e32 v63, v37, v177
	v_fmac_f32_e32 v63, v38, v178
	v_fmac_f32_e32 v63, v39, v179
	v_cndmask_b32_e64 v56, v51, v63, s[8:9]
	v_cndmask_b32_e64 v57, v63, v51, s[8:9]
	s_nop 0
	s_nop 0
	v_add_f32_dpp v66, v57, v56 quad_perm:[1,0,3,2] row_mask:0xf bank_mask:0xf bound_ctrl:1
	v_cndmask_b32_e64 v56, v62, v66, s[10:11]
	v_cndmask_b32_e64 v57, v66, v62, s[10:11]
	s_nop 0
	s_nop 0
	v_add_f32_dpp v64, v57, v56 quad_perm:[2,3,0,1] row_mask:0xf bank_mask:0xf bound_ctrl:1
	v_add_f32_dpp v46, v54, v54 row_shl:4 row_mask:0xf bank_mask:0x5
	s_nop 0
	s_nop 0
	v_add_f32_dpp v46, v64, v64 row_shr:4 row_mask:0xf bank_mask:0xa
	v_add_f32_dpp v48, v49, v49 row_ror:8 row_mask:0xf bank_mask:0x3
	s_nop 0
	s_nop 0
	v_add_f32_dpp v48, v46, v46 row_ror:8 row_mask:0xf bank_mask:0xc
	ds_write_b32 v122, v48 offset:2048
	s_cbranch_vccnz .LBB0_183
	s_and_saveexec_b64 s[2:3], s[42:43]
	s_cbranch_execz .Lsc_nost
	v_lshl_add_u64 v[52:53], s[88:89], 0, v[100:101]
	global_store_dword v[52:53], v245, off
